# scan: per-tile column-scaled state (no per-step decay multiply), exact f32 reformulation; rebase once per 8 steps
# speedup vs baseline: 1.0806x; 1.0149x over previous
; template <int MODE>
; __device__ __forceinline__ void scan_unit(const Params& p, int l, int chain, int chunk, float* wl) {
;     ...
;     asm volatile("s_waitcnt lgkmcnt(0)" ::: "memory");
; #pragma unroll
;     for (int s = 0; s < TS; ++s) {
;       float e = (float)pe[s], kk = (float)pkk[s], a = (float)pa[s];
;       lw[s * 64 + lane] = __expf(-e);
;       lkk[s * 64 + lane] = kk;
;       lbb[s * 64 + lane] = kk * a;
;       if (MODE >= 1) {
;         lkd[s * 64 + lane] = (float)pk[s] * (1.0f + (a - 1.0f) * ka);
;         lv[s * 64 + lane] = (float)pv[s];
;       }
;       if (MODE == 2) lr[s * 64 + lane] = (float)pr[s];
;     }
;     asm volatile("s_waitcnt lgkmcnt(0)" ::: "memory");
.LBB0_832:
	s_waitcnt lgkmcnt(0)
	s_waitcnt vmcnt(35)
	v_cvt_f32_f16_e32 v246, v104
	v_mov_b32_e32 v244, v246
	v_mul_f32_e32 v247, 0xbfb8aa3b, v244
	v_cvt_f32_f16_e32 v250, v105
	v_exp_f32_e32 v248, v247
	v_cvt_f32_f16_e32 v251, v106
	v_exp_f32_e64 v249, -v247
	v_cvt_f32_f16_e32 v252, v107
	ds_write_b32 v91, v250 offset:4096
	v_mul_f32_e32 v253, v250, v251
	v_add_f32_e32 v251, -1.0, v251
	v_mul_f32_e32 v253, v253, v249
	ds_write_b32 v91, v253 offset:6144
	v_fma_f32 v251, v103, v251, 1.0
	v_cvt_f32_f16_e32 v254, v108
	v_mul_f32_e32 v252, v251, v252
	v_mul_f32_e32 v252, v252, v249
	ds_write_b32 v91, v252 offset:2048
	ds_write_b32 v91, v254 offset:10240
	ds_write_b32 v91, v248 offset:0
	v_mov_b32_e32 v245, v248
	s_waitcnt vmcnt(30)
	v_cvt_f32_f16_e32 v246, v109
	v_add_f32_e32 v244, v244, v246
	v_mul_f32_e32 v247, 0xbfb8aa3b, v244
	v_cvt_f32_f16_e32 v250, v110
	v_exp_f32_e32 v248, v247
	v_cvt_f32_f16_e32 v251, v111
	v_exp_f32_e64 v249, -v247
	v_cvt_f32_f16_e32 v252, v112
	v_mul_f32_e32 v255, v250, v245
	ds_write_b32 v91, v255 offset:4352
	v_mul_f32_e32 v253, v250, v251
	v_add_f32_e32 v251, -1.0, v251
	v_mul_f32_e32 v253, v253, v249
	ds_write_b32 v91, v253 offset:6400
	v_fma_f32 v251, v103, v251, 1.0
	v_cvt_f32_f16_e32 v254, v113
	v_mul_f32_e32 v252, v251, v252
	v_mul_f32_e32 v252, v252, v249
	ds_write_b32 v91, v252 offset:2304
	ds_write_b32 v91, v254 offset:10496
	ds_write_b32 v91, v248 offset:256
	v_mov_b32_e32 v245, v248
	s_waitcnt vmcnt(25)
	v_cvt_f32_f16_e32 v246, v114
	v_add_f32_e32 v244, v244, v246
	v_mul_f32_e32 v247, 0xbfb8aa3b, v244
	v_cvt_f32_f16_e32 v250, v115
	v_exp_f32_e32 v248, v247
	v_cvt_f32_f16_e32 v251, v116
	v_exp_f32_e64 v249, -v247
	v_cvt_f32_f16_e32 v252, v117
	v_mul_f32_e32 v255, v250, v245
	ds_write_b32 v91, v255 offset:4608
	v_mul_f32_e32 v253, v250, v251
	v_add_f32_e32 v251, -1.0, v251
	v_mul_f32_e32 v253, v253, v249
	ds_write_b32 v91, v253 offset:6656
	v_fma_f32 v251, v103, v251, 1.0
	v_cvt_f32_f16_e32 v254, v118
	v_mul_f32_e32 v252, v251, v252
	v_mul_f32_e32 v252, v252, v249
	ds_write_b32 v91, v252 offset:2560
	ds_write_b32 v91, v254 offset:10752
	ds_write_b32 v91, v248 offset:512
	v_mov_b32_e32 v245, v248
	s_waitcnt vmcnt(20)
	v_cvt_f32_f16_e32 v246, v119
	v_add_f32_e32 v244, v244, v246
	v_mul_f32_e32 v247, 0xbfb8aa3b, v244
	v_cvt_f32_f16_e32 v250, v120
	v_exp_f32_e32 v248, v247
	v_cvt_f32_f16_e32 v251, v121
	v_exp_f32_e64 v249, -v247
	v_cvt_f32_f16_e32 v252, v122
	v_mul_f32_e32 v255, v250, v245
	ds_write_b32 v91, v255 offset:4864
	v_mul_f32_e32 v253, v250, v251
	v_add_f32_e32 v251, -1.0, v251
	v_mul_f32_e32 v253, v253, v249
	ds_write_b32 v91, v253 offset:6912
	v_fma_f32 v251, v103, v251, 1.0
	v_cvt_f32_f16_e32 v254, v123
	v_mul_f32_e32 v252, v251, v252
	v_mul_f32_e32 v252, v252, v249
	ds_write_b32 v91, v252 offset:2816
	ds_write_b32 v91, v254 offset:11008
	ds_write_b32 v91, v248 offset:768
	v_mov_b32_e32 v245, v248
	s_waitcnt vmcnt(15)
	v_cvt_f32_f16_e32 v246, v124
	v_add_f32_e32 v244, v244, v246
	v_mul_f32_e32 v247, 0xbfb8aa3b, v244
	v_cvt_f32_f16_e32 v250, v125
	v_exp_f32_e32 v248, v247
	v_cvt_f32_f16_e32 v251, v126
	v_exp_f32_e64 v249, -v247
	v_cvt_f32_f16_e32 v252, v127
	v_mul_f32_e32 v255, v250, v245
	ds_write_b32 v91, v255 offset:5120
	v_mul_f32_e32 v253, v250, v251
	v_add_f32_e32 v251, -1.0, v251
	v_mul_f32_e32 v253, v253, v249
	ds_write_b32 v91, v253 offset:7168
	v_fma_f32 v251, v103, v251, 1.0
	v_cvt_f32_f16_e32 v254, v128
	v_mul_f32_e32 v252, v251, v252
	v_mul_f32_e32 v252, v252, v249
	ds_write_b32 v91, v252 offset:3072
	ds_write_b32 v91, v254 offset:11264
	ds_write_b32 v91, v248 offset:1024
	v_mov_b32_e32 v245, v248
	s_waitcnt vmcnt(10)
	v_cvt_f32_f16_e32 v246, v129
	v_add_f32_e32 v244, v244, v246
	v_mul_f32_e32 v247, 0xbfb8aa3b, v244
	v_cvt_f32_f16_e32 v250, v130
	v_exp_f32_e32 v248, v247
	v_cvt_f32_f16_e32 v251, v131
	v_exp_f32_e64 v249, -v247
	v_cvt_f32_f16_e32 v252, v132
	v_mul_f32_e32 v255, v250, v245
	ds_write_b32 v91, v255 offset:5376
	v_mul_f32_e32 v253, v250, v251
	v_add_f32_e32 v251, -1.0, v251
	v_mul_f32_e32 v253, v253, v249
	ds_write_b32 v91, v253 offset:7424
	v_fma_f32 v251, v103, v251, 1.0
	v_cvt_f32_f16_e32 v254, v133
	v_mul_f32_e32 v252, v251, v252
	v_mul_f32_e32 v252, v252, v249
	ds_write_b32 v91, v252 offset:3328
	ds_write_b32 v91, v254 offset:11520
	ds_write_b32 v91, v248 offset:1280
	v_mov_b32_e32 v245, v248
	s_waitcnt vmcnt(5)
	v_cvt_f32_f16_e32 v246, v134
	v_add_f32_e32 v244, v244, v246
	v_mul_f32_e32 v247, 0xbfb8aa3b, v244
	v_cvt_f32_f16_e32 v250, v135
	v_exp_f32_e32 v248, v247
	v_cvt_f32_f16_e32 v251, v136
	v_exp_f32_e64 v249, -v247
	v_cvt_f32_f16_e32 v252, v137
	v_mul_f32_e32 v255, v250, v245
	ds_write_b32 v91, v255 offset:5632
	v_mul_f32_e32 v253, v250, v251
	v_add_f32_e32 v251, -1.0, v251
	v_mul_f32_e32 v253, v253, v249
	ds_write_b32 v91, v253 offset:7680
	v_fma_f32 v251, v103, v251, 1.0
	v_cvt_f32_f16_e32 v254, v138
	v_mul_f32_e32 v252, v251, v252
	v_mul_f32_e32 v252, v252, v249
	ds_write_b32 v91, v252 offset:3584
	ds_write_b32 v91, v254 offset:11776
	ds_write_b32 v91, v248 offset:1536
	v_mov_b32_e32 v245, v248
	s_waitcnt vmcnt(0)
	v_cvt_f32_f16_e32 v246, v139
	v_add_f32_e32 v244, v244, v246
	v_mul_f32_e32 v247, 0xbfb8aa3b, v244
	v_cvt_f32_f16_e32 v250, v140
	v_exp_f32_e32 v248, v247
	v_cvt_f32_f16_e32 v251, v141
	v_exp_f32_e64 v249, -v247
	v_cvt_f32_f16_e32 v252, v142
	v_mul_f32_e32 v255, v250, v245
	ds_write_b32 v91, v255 offset:5888
	v_mul_f32_e32 v253, v250, v251
	v_add_f32_e32 v251, -1.0, v251
	v_mul_f32_e32 v253, v253, v249
	ds_write_b32 v91, v253 offset:7936
	v_fma_f32 v251, v103, v251, 1.0
	v_cvt_f32_f16_e32 v254, v143
	v_mul_f32_e32 v252, v251, v252
	v_mul_f32_e32 v252, v252, v249
	ds_write_b32 v91, v252 offset:3840
	ds_write_b32 v91, v254 offset:12032
	ds_write_b32 v91, v248 offset:1792
	v_mov_b32_e32 v245, v248
	s_waitcnt lgkmcnt(0)
	s_mov_b32 s24, s21
	s_add_i32 s21, s21, 1
	s_cmp_eq_u32 s24, 31
	s_cbranch_scc1 .LBB0_834
	s_lshl_b32 s24, s21, 3
	s_add_i32 s24, s24, s20
	s_not_b32 s25, s24
	s_add_i32 s25, s18, s25
	s_and_b64 s[34:35], s[10:11], exec
	s_cselect_b32 s25, s24, s25
	s_add_i32 s25, s25, s19
	v_mad_i64_i32 v[104:105], s[34:35], s25, v189, v[84:85]
	s_xor_b32 s34, s24, -2
	s_or_b32 s25, s24, 1
	s_add_i32 s38, s34, s18
	v_lshlrev_b64 v[108:109], 1, v[104:105]
	s_and_b64 s[34:35], s[10:11], exec
	v_lshl_add_u64 v[104:105], v[86:87], 0, v[108:109]
	v_lshl_add_u64 v[106:107], v[68:69], 0, v[108:109]
	s_cselect_b32 s25, s25, s38
	global_load_ushort v104, v[104:105], off
	v_lshl_add_u64 v[110:111], v[66:67], 0, v[108:109]
	global_load_ushort v105, v[106:107], off
	v_lshl_add_u64 v[106:107], v[88:89], 0, v[108:109]
	s_add_i32 s25, s25, s19
	global_load_ushort v106, v[106:107], off
	v_lshl_add_u64 v[108:109], v[74:75], 0, v[108:109]
	global_load_ushort v107, v[110:111], off
	v_mad_i64_i32 v[110:111], s[34:35], s25, v189, v[84:85]
	s_xor_b32 s34, s24, -3
	v_lshlrev_b64 v[114:115], 1, v[110:111]
	s_or_b32 s25, s24, 2
	s_add_i32 s38, s34, s18
	v_lshl_add_u64 v[110:111], v[86:87], 0, v[114:115]
	s_and_b64 s[34:35], s[10:11], exec
	global_load_ushort v108, v[108:109], off
	v_lshl_add_u64 v[112:113], v[88:89], 0, v[114:115]
	global_load_ushort v109, v[110:111], off
	v_lshl_add_u64 v[110:111], v[68:69], 0, v[114:115]
	s_cselect_b32 s25, s25, s38
	global_load_ushort v110, v[110:111], off
	s_add_i32 s25, s25, s19
	global_load_ushort v111, v[112:113], off
	v_lshl_add_u64 v[112:113], v[66:67], 0, v[114:115]
	v_lshl_add_u64 v[114:115], v[74:75], 0, v[114:115]
	global_load_ushort v112, v[112:113], off
	s_nop 0
	global_load_ushort v113, v[114:115], off
	v_mad_i64_i32 v[114:115], s[34:35], s25, v189, v[84:85]
	s_xor_b32 s34, s24, -4
	s_or_b32 s25, s24, 3
	s_add_i32 s38, s34, s18
	v_lshlrev_b64 v[118:119], 1, v[114:115]
	s_and_b64 s[34:35], s[10:11], exec
	v_lshl_add_u64 v[114:115], v[86:87], 0, v[118:119]
	v_lshl_add_u64 v[116:117], v[68:69], 0, v[118:119]
	s_cselect_b32 s25, s25, s38
	global_load_ushort v114, v[114:115], off
	v_lshl_add_u64 v[120:121], v[66:67], 0, v[118:119]
	global_load_ushort v115, v[116:117], off
	v_lshl_add_u64 v[116:117], v[88:89], 0, v[118:119]
	s_add_i32 s25, s25, s19
	global_load_ushort v116, v[116:117], off
	v_lshl_add_u64 v[118:119], v[74:75], 0, v[118:119]
	global_load_ushort v117, v[120:121], off
	v_mad_i64_i32 v[120:121], s[34:35], s25, v189, v[84:85]
	s_xor_b32 s34, s24, -5
	v_lshlrev_b64 v[124:125], 1, v[120:121]
	s_or_b32 s25, s24, 4
	s_add_i32 s38, s34, s18
	v_lshl_add_u64 v[120:121], v[86:87], 0, v[124:125]
	s_and_b64 s[34:35], s[10:11], exec
	global_load_ushort v118, v[118:119], off
	v_lshl_add_u64 v[122:123], v[88:89], 0, v[124:125]
	global_load_ushort v119, v[120:121], off
	v_lshl_add_u64 v[120:121], v[68:69], 0, v[124:125]
	s_cselect_b32 s25, s25, s38
	global_load_ushort v120, v[120:121], off
	s_add_i32 s25, s25, s19
	global_load_ushort v121, v[122:123], off
	v_lshl_add_u64 v[122:123], v[66:67], 0, v[124:125]
	v_lshl_add_u64 v[124:125], v[74:75], 0, v[124:125]
	global_load_ushort v122, v[122:123], off
	s_nop 0
	global_load_ushort v123, v[124:125], off
	v_mad_i64_i32 v[124:125], s[34:35], s25, v189, v[84:85]
	s_xor_b32 s34, s24, -6
	s_or_b32 s25, s24, 5
	s_add_i32 s38, s34, s18
	v_lshlrev_b64 v[128:129], 1, v[124:125]
	s_and_b64 s[34:35], s[10:11], exec
	v_lshl_add_u64 v[124:125], v[86:87], 0, v[128:129]
	v_lshl_add_u64 v[126:127], v[68:69], 0, v[128:129]
	s_cselect_b32 s25, s25, s38
	global_load_ushort v124, v[124:125], off
	v_lshl_add_u64 v[130:131], v[66:67], 0, v[128:129]
	global_load_ushort v125, v[126:127], off
	v_lshl_add_u64 v[126:127], v[88:89], 0, v[128:129]
	s_add_i32 s25, s25, s19
	global_load_ushort v126, v[126:127], off
	v_lshl_add_u64 v[128:129], v[74:75], 0, v[128:129]
	global_load_ushort v127, v[130:131], off
	v_mad_i64_i32 v[130:131], s[34:35], s25, v189, v[84:85]
	s_xor_b32 s34, s24, -7
	v_lshlrev_b64 v[134:135], 1, v[130:131]
	s_or_b32 s25, s24, 6
	s_add_i32 s38, s34, s18
	v_lshl_add_u64 v[130:131], v[86:87], 0, v[134:135]
	s_and_b64 s[34:35], s[10:11], exec
	global_load_ushort v128, v[128:129], off
	v_lshl_add_u64 v[132:133], v[88:89], 0, v[134:135]
	global_load_ushort v129, v[130:131], off
	v_lshl_add_u64 v[130:131], v[68:69], 0, v[134:135]
	s_cselect_b32 s25, s25, s38
	global_load_ushort v130, v[130:131], off
	s_add_i32 s25, s25, s19
	global_load_ushort v131, v[132:133], off
	v_lshl_add_u64 v[132:133], v[66:67], 0, v[134:135]
	v_lshl_add_u64 v[134:135], v[74:75], 0, v[134:135]
	global_load_ushort v132, v[132:133], off
	s_nop 0
	global_load_ushort v133, v[134:135], off
	v_mad_i64_i32 v[134:135], s[34:35], s25, v189, v[84:85]
	s_or_b32 s34, s24, 7
	s_xor_b32 s24, s24, -8
	s_add_i32 s35, s24, s18
	v_lshlrev_b64 v[138:139], 1, v[134:135]
	s_and_b64 s[24:25], s[10:11], exec
	v_lshl_add_u64 v[134:135], v[86:87], 0, v[138:139]
	v_lshl_add_u64 v[136:137], v[68:69], 0, v[138:139]
	s_cselect_b32 s24, s34, s35
	global_load_ushort v134, v[134:135], off
	v_lshl_add_u64 v[140:141], v[66:67], 0, v[138:139]
	global_load_ushort v135, v[136:137], off
	v_lshl_add_u64 v[136:137], v[88:89], 0, v[138:139]
	s_add_i32 s24, s24, s19
	global_load_ushort v136, v[136:137], off
	v_lshl_add_u64 v[138:139], v[74:75], 0, v[138:139]
	global_load_ushort v137, v[140:141], off
	v_mad_i64_i32 v[140:141], s[24:25], s24, v189, v[84:85]
	v_lshlrev_b64 v[144:145], 1, v[140:141]
	v_lshl_add_u64 v[140:141], v[86:87], 0, v[144:145]
	global_load_ushort v138, v[138:139], off
	v_lshl_add_u64 v[142:143], v[88:89], 0, v[144:145]
	global_load_ushort v139, v[140:141], off
	v_lshl_add_u64 v[140:141], v[68:69], 0, v[144:145]
	global_load_ushort v140, v[140:141], off
	s_nop 0
	global_load_ushort v141, v[142:143], off
	v_lshl_add_u64 v[142:143], v[66:67], 0, v[144:145]
	v_lshl_add_u64 v[144:145], v[74:75], 0, v[144:145]
	global_load_ushort v142, v[142:143], off
	s_nop 0
	global_load_ushort v143, v[144:145], off

; template <int MODE>
; __device__ __forceinline__ void scan_unit(const Params& p, int l, int chain, int chunk, float* wl) {
;     ...
;     for (int s = 0; s < TS; ++s) {
;       f32x2 kk2[4], w2[4], b2[4], k2[4], r2[4];
;       float v8[8];
;       ld8(lkk + s * 64 + 8 * cj, kk2);
;       ld8(lw + s * 64 + 8 * cj, w2);
;       ld8(lbb + s * 64 + 8 * cj, b2);
;       if (MODE >= 1) {
;         ld8(lkd + s * 64 + 8 * cj, k2);
;         float4 t0 = *(const float4*)(lv + s * 64 + 8 * ri), t1 = *(const float4*)(lv + s * 64 + 8 * ri + 4);
;         v8[0] = t0.x; v8[1] = t0.y; v8[2] = t0.z; v8[3] = t0.w; v8[4] = t1.x; v8[5] = t1.y; v8[6] = t1.z; v8[7] = t1.w;
;       }
;       if (MODE == 2) ld8(lr + s * 64 + 8 * cj, r2);
;       float t[8];
; #pragma unroll
;       for (int a = 0; a < 8; ++a) {
;         f32x2 acc = S[a][0] * kk2[0];
;         acc = S[a][1] * kk2[1] + acc;
;         acc = S[a][2] * kk2[2] + acc;
;         acc = S[a][3] * kk2[3] + acc;
;         t[a] = acc.x + acc.y;
;       }
;       red8x8(t);
;       float yp[8];
; #pragma unroll
;       for (int a = 0; a < 8; ++a) {
;         const float ns = -t[a];
;         const f32x2 ns2 = f32x2{ns, ns};
;         f32x2 ya = f32x2{0.f, 0.f};
; #pragma unroll
;         for (int q = 0; q < 4; ++q) {
;           f32x2 sn = S[a][q] * w2[q] + ns2 * b2[q];
;           if (MODE >= 1) sn = f32x2{v8[a], v8[a]} * k2[q] + sn;
;           S[a][q] = sn;
;           if (MODE == 2) ya = sn * r2[q] + ya;
;         }
;         yp[a] = ya.x + ya.y;
;       }
.LBB0_835:
	v_add_u32_e32 v164, s24, v92
	ds_read_b128 v[144:147], v164 offset:4096
	ds_read_b128 v[148:151], v164 offset:4112
	ds_read_b128 v[152:155], v164
	ds_read_b128 v[156:159], v164 offset:16
	ds_read_b128 v[160:163], v164 offset:6144
	ds_read_b128 v[166:169], v164 offset:6160
	ds_read_b128 v[192:195], v164 offset:2048
	ds_read_b128 v[196:199], v164 offset:2064
	s_waitcnt lgkmcnt(7)
	v_pk_mul_f32 v[208:209], v[46:47], v[146:147]
	v_add_u32_e32 v164, s24, v93
	v_pk_fma_f32 v[208:209], v[44:45], v[144:145], v[208:209]
	ds_read_b128 v[200:203], v164
	ds_read_b128 v[204:207], v164 offset:16
	s_waitcnt lgkmcnt(8)
	v_pk_fma_f32 v[208:209], v[28:29], v[148:149], v[208:209]
	s_addk_i32 s24, 0x100
	v_pk_fma_f32 v[208:209], v[30:31], v[150:151], v[208:209]
	s_cmpk_eq_i32 s24, 0x800
	v_add_f32_e32 v164, v208, v209
	v_pk_mul_f32 v[208:209], v[18:19], v[146:147]
	s_nop 0
	v_pk_fma_f32 v[208:209], v[16:17], v[144:145], v[208:209]
	s_nop 0
	v_pk_fma_f32 v[208:209], v[8:9], v[148:149], v[208:209]
	s_nop 0
	v_pk_fma_f32 v[208:209], v[10:11], v[150:151], v[208:209]
	s_nop 0
	v_add_f32_e32 v170, v208, v209
	v_pk_mul_f32 v[208:209], v[6:7], v[146:147]
	s_nop 0
	v_pk_fma_f32 v[208:209], v[4:5], v[144:145], v[208:209]
	s_nop 0
	v_pk_fma_f32 v[208:209], v[0:1], v[148:149], v[208:209]
	s_nop 0
	v_pk_fma_f32 v[208:209], v[2:3], v[150:151], v[208:209]
	s_nop 0
	v_add_f32_e32 v210, v208, v209
	v_pk_mul_f32 v[208:209], v[62:63], v[146:147]
	s_nop 0
	v_pk_fma_f32 v[208:209], v[60:61], v[144:145], v[208:209]
	s_nop 0
	v_pk_fma_f32 v[208:209], v[56:57], v[148:149], v[208:209]
	s_nop 0
	v_pk_fma_f32 v[208:209], v[58:59], v[150:151], v[208:209]
	s_nop 0
	v_add_f32_e32 v211, v208, v209
	v_pk_mul_f32 v[208:209], v[54:55], v[146:147]
	s_nop 0
	v_pk_fma_f32 v[208:209], v[52:53], v[144:145], v[208:209]
	s_nop 0
	v_pk_fma_f32 v[208:209], v[48:49], v[148:149], v[208:209]
	s_nop 0
	v_pk_fma_f32 v[208:209], v[50:51], v[150:151], v[208:209]
	s_nop 0
	v_add_f32_e32 v212, v208, v209
	v_pk_mul_f32 v[208:209], v[42:43], v[146:147]
	s_nop 0
	v_pk_fma_f32 v[208:209], v[40:41], v[144:145], v[208:209]
	s_nop 0
	v_pk_fma_f32 v[208:209], v[36:37], v[148:149], v[208:209]
	s_nop 0
	v_pk_fma_f32 v[208:209], v[38:39], v[150:151], v[208:209]
	s_nop 0
	v_add_f32_e32 v213, v208, v209
	v_pk_mul_f32 v[208:209], v[34:35], v[146:147]
	v_pk_mul_f32 v[146:147], v[22:23], v[146:147]
	v_pk_fma_f32 v[208:209], v[32:33], v[144:145], v[208:209]
	v_pk_fma_f32 v[144:145], v[20:21], v[144:145], v[146:147]
	v_pk_fma_f32 v[208:209], v[24:25], v[148:149], v[208:209]
	v_pk_fma_f32 v[144:145], v[12:13], v[148:149], v[144:145]
	v_pk_fma_f32 v[208:209], v[26:27], v[150:151], v[208:209]
	v_pk_fma_f32 v[144:145], v[14:15], v[150:151], v[144:145]
	v_add_f32_e32 v208, v208, v209
	v_add_f32_e32 v144, v144, v145
	v_add_f32_dpp v145, v164, v164 quad_perm:[1,0,3,2] row_mask:0xf bank_mask:0xf bound_ctrl:1
	v_add_f32_dpp v146, v170, v170 quad_perm:[1,0,3,2] row_mask:0xf bank_mask:0xf bound_ctrl:1
	v_add_f32_dpp v144, v144, v144 quad_perm:[1,0,3,2] row_mask:0xf bank_mask:0xf bound_ctrl:1
	v_add_f32_dpp v145, v145, v145 quad_perm:[2,3,0,1] row_mask:0xf bank_mask:0xf bound_ctrl:1
	v_add_f32_dpp v149, v212, v212 quad_perm:[1,0,3,2] row_mask:0xf bank_mask:0xf bound_ctrl:1
	v_add_f32_dpp v209, v144, v144 quad_perm:[2,3,0,1] row_mask:0xf bank_mask:0xf bound_ctrl:1
	v_add_f32_dpp v144, v145, v145 row_half_mirror row_mask:0xf bank_mask:0xf bound_ctrl:1
	v_add_f32_dpp v150, v213, v213 quad_perm:[1,0,3,2] row_mask:0xf bank_mask:0xf bound_ctrl:1
	s_waitcnt lgkmcnt(5)
	v_pk_fma_f32 v[44:45], v[160:161], v[144:145], v[44:45] op_sel_hi:[1,0,1] neg_lo:[0,1,0] neg_hi:[0,1,0]
	v_add_f32_dpp v147, v210, v210 quad_perm:[1,0,3,2] row_mask:0xf bank_mask:0xf bound_ctrl:1
	v_add_f32_dpp v146, v146, v146 quad_perm:[2,3,0,1] row_mask:0xf bank_mask:0xf bound_ctrl:1
	v_pk_fma_f32 v[46:47], v[162:163], v[144:145], v[46:47] op_sel_hi:[1,0,1] neg_lo:[0,1,0] neg_hi:[0,1,0]
	v_add_f32_dpp v147, v147, v147 quad_perm:[2,3,0,1] row_mask:0xf bank_mask:0xf bound_ctrl:1
	v_add_f32_dpp v146, v146, v146 row_half_mirror row_mask:0xf bank_mask:0xf bound_ctrl:1
	s_waitcnt lgkmcnt(4)
	v_pk_fma_f32 v[28:29], v[166:167], v[144:145], v[28:29] op_sel_hi:[1,0,1] neg_lo:[0,1,0] neg_hi:[0,1,0]
	v_pk_fma_f32 v[30:31], v[168:169], v[144:145], v[30:31] op_sel_hi:[1,0,1] neg_lo:[0,1,0] neg_hi:[0,1,0]
	v_add_f32_dpp v148, v211, v211 quad_perm:[1,0,3,2] row_mask:0xf bank_mask:0xf bound_ctrl:1
	v_pk_fma_f32 v[16:17], v[160:161], v[146:147], v[16:17] op_sel_hi:[1,0,1] neg_lo:[0,1,0] neg_hi:[0,1,0]
	v_add_f32_dpp v151, v208, v208 quad_perm:[1,0,3,2] row_mask:0xf bank_mask:0xf bound_ctrl:1
	v_pk_fma_f32 v[18:19], v[162:163], v[146:147], v[18:19] op_sel_hi:[1,0,1] neg_lo:[0,1,0] neg_hi:[0,1,0]
	v_add_f32_dpp v164, v148, v148 quad_perm:[2,3,0,1] row_mask:0xf bank_mask:0xf bound_ctrl:1
	v_pk_fma_f32 v[8:9], v[166:167], v[146:147], v[8:9] op_sel_hi:[1,0,1] neg_lo:[0,1,0] neg_hi:[0,1,0]
	v_add_f32_dpp v149, v149, v149 quad_perm:[2,3,0,1] row_mask:0xf bank_mask:0xf bound_ctrl:1
	v_add_f32_dpp v170, v150, v150 quad_perm:[2,3,0,1] row_mask:0xf bank_mask:0xf bound_ctrl:1
	v_add_f32_dpp v151, v151, v151 quad_perm:[2,3,0,1] row_mask:0xf bank_mask:0xf bound_ctrl:1
	v_add_f32_dpp v148, v147, v147 row_half_mirror row_mask:0xf bank_mask:0xf bound_ctrl:1
	v_add_f32_dpp v150, v164, v164 row_half_mirror row_mask:0xf bank_mask:0xf bound_ctrl:1
	v_pk_fma_f32 v[10:11], v[168:169], v[146:147], v[10:11] op_sel_hi:[1,0,1] neg_lo:[0,1,0] neg_hi:[0,1,0]
	v_pk_fma_f32 v[60:61], v[160:161], v[150:151], v[60:61] op_sel_hi:[1,0,1] neg_lo:[0,1,0] neg_hi:[0,1,0]
	v_pk_fma_f32 v[4:5], v[160:161], v[148:149], v[4:5] op_sel_hi:[1,0,1] neg_lo:[0,1,0] neg_hi:[0,1,0]
	v_pk_fma_f32 v[6:7], v[162:163], v[148:149], v[6:7] op_sel_hi:[1,0,1] neg_lo:[0,1,0] neg_hi:[0,1,0]
	v_pk_fma_f32 v[62:63], v[162:163], v[150:151], v[62:63] op_sel_hi:[1,0,1] neg_lo:[0,1,0] neg_hi:[0,1,0]
	v_pk_fma_f32 v[0:1], v[166:167], v[148:149], v[0:1] op_sel_hi:[1,0,1] neg_lo:[0,1,0] neg_hi:[0,1,0]
	v_pk_fma_f32 v[56:57], v[166:167], v[150:151], v[56:57] op_sel_hi:[1,0,1] neg_lo:[0,1,0] neg_hi:[0,1,0]
	v_pk_fma_f32 v[2:3], v[168:169], v[148:149], v[2:3] op_sel_hi:[1,0,1] neg_lo:[0,1,0] neg_hi:[0,1,0]
	v_pk_fma_f32 v[58:59], v[168:169], v[150:151], v[58:59] op_sel_hi:[1,0,1] neg_lo:[0,1,0] neg_hi:[0,1,0]
	v_add_f32_dpp v164, v149, v149 row_half_mirror row_mask:0xf bank_mask:0xf bound_ctrl:1
	s_waitcnt lgkmcnt(1)
; template <int MODE>
; __device__ __forceinline__ void scan_unit(const Params& p, int l, int chain, int chunk, float* wl) {
;     ...
;       for (int a = 0; a < 8; ++a) {
;         f32x2 acc = S[a][0] * kk2[0];
;         acc = S[a][1] * kk2[1] + acc;
;         acc = S[a][2] * kk2[2] + acc;
;         acc = S[a][3] * kk2[3] + acc;
;         t[a] = acc.x + acc.y;
;       }
;       red8x8(t);
;       float yp[8];
; #pragma unroll
;       for (int a = 0; a < 8; ++a) {
;         const float ns = -t[a];
;         const f32x2 ns2 = f32x2{ns, ns};
;         f32x2 ya = f32x2{0.f, 0.f};
; #pragma unroll
;         for (int q = 0; q < 4; ++q) {
;           f32x2 sn = S[a][q] * w2[q] + ns2 * b2[q];
;           if (MODE >= 1) sn = f32x2{v8[a], v8[a]} * k2[q] + sn;
;           S[a][q] = sn;
;           if (MODE == 2) ya = sn * r2[q] + ya;
;         }
;         yp[a] = ya.x + ya.y;
;       }
;     ...
;   if (MODE == 1) {
;     float* dst = PQ + ((size_t)(chain * NCHUNK + chunk) * 2 + 1) * 4096 + (8 * ri) * 64 + 8 * cj;
; #pragma unroll
;     for (int a = 0; a < 8; ++a) {
;       *(float4*)(dst + a * 64) = make_float4(S[a][0].x, S[a][0].y, S[a][1].x, S[a][1].y);
;       *(float4*)(dst + a * 64 + 4) = make_float4(S[a][2].x, S[a][2].y, S[a][3].x, S[a][3].y);
;     }
;   }
	v_mov_b32_e32 v144, v203
	v_pk_fma_f32 v[60:61], v[192:193], v[144:145], v[60:61] op_sel_hi:[1,0,1]
	v_pk_fma_f32 v[62:63], v[194:195], v[144:145], v[62:63] op_sel_hi:[1,0,1]
	v_pk_fma_f32 v[56:57], v[196:197], v[144:145], v[56:57] op_sel_hi:[1,0,1]
	v_pk_fma_f32 v[58:59], v[198:199], v[144:145], v[58:59] op_sel_hi:[1,0,1]
	v_pk_fma_f32 v[52:53], v[160:161], v[164:165], v[52:53] op_sel_hi:[1,0,1] neg_lo:[0,1,0] neg_hi:[0,1,0]
	v_add_f32_dpp v170, v170, v170 row_half_mirror row_mask:0xf bank_mask:0xf bound_ctrl:1
	v_pk_fma_f32 v[54:55], v[162:163], v[164:165], v[54:55] op_sel_hi:[1,0,1] neg_lo:[0,1,0] neg_hi:[0,1,0]
	v_add_f32_dpp v208, v151, v151 row_half_mirror row_mask:0xf bank_mask:0xf bound_ctrl:1
	v_pk_fma_f32 v[48:49], v[166:167], v[164:165], v[48:49] op_sel_hi:[1,0,1] neg_lo:[0,1,0] neg_hi:[0,1,0]
	v_add_f32_dpp v210, v209, v209 row_half_mirror row_mask:0xf bank_mask:0xf bound_ctrl:1
	v_pk_fma_f32 v[50:51], v[168:169], v[164:165], v[50:51] op_sel_hi:[1,0,1] neg_lo:[0,1,0] neg_hi:[0,1,0]
	v_pk_fma_f32 v[20:21], v[160:161], v[210:211], v[20:21] op_sel_hi:[1,0,1] neg_lo:[0,1,0] neg_hi:[0,1,0]
	v_pk_fma_f32 v[40:41], v[160:161], v[170:171], v[40:41] op_sel_hi:[1,0,1] neg_lo:[0,1,0] neg_hi:[0,1,0]
	v_pk_fma_f32 v[42:43], v[162:163], v[170:171], v[42:43] op_sel_hi:[1,0,1] neg_lo:[0,1,0] neg_hi:[0,1,0]
	v_pk_fma_f32 v[22:23], v[162:163], v[210:211], v[22:23] op_sel_hi:[1,0,1] neg_lo:[0,1,0] neg_hi:[0,1,0]
	v_pk_fma_f32 v[36:37], v[166:167], v[170:171], v[36:37] op_sel_hi:[1,0,1] neg_lo:[0,1,0] neg_hi:[0,1,0]
	v_pk_fma_f32 v[38:39], v[168:169], v[170:171], v[38:39] op_sel_hi:[1,0,1] neg_lo:[0,1,0] neg_hi:[0,1,0]
	v_pk_fma_f32 v[12:13], v[166:167], v[210:211], v[12:13] op_sel_hi:[1,0,1] neg_lo:[0,1,0] neg_hi:[0,1,0]
	v_pk_fma_f32 v[32:33], v[160:161], v[208:209], v[32:33] op_sel_hi:[1,0,1] neg_lo:[0,1,0] neg_hi:[0,1,0]
	v_pk_fma_f32 v[34:35], v[162:163], v[208:209], v[34:35] op_sel_hi:[1,0,1] neg_lo:[0,1,0] neg_hi:[0,1,0]
	v_pk_fma_f32 v[14:15], v[168:169], v[210:211], v[14:15] op_sel_hi:[1,0,1] neg_lo:[0,1,0] neg_hi:[0,1,0]
	v_pk_fma_f32 v[24:25], v[166:167], v[208:209], v[24:25] op_sel_hi:[1,0,1] neg_lo:[0,1,0] neg_hi:[0,1,0]
	v_pk_fma_f32 v[26:27], v[168:169], v[208:209], v[26:27] op_sel_hi:[1,0,1] neg_lo:[0,1,0] neg_hi:[0,1,0]
	s_waitcnt lgkmcnt(0)
	v_mov_b32_e32 v144, v207
	v_pk_fma_f32 v[44:45], v[192:193], v[200:201], v[44:45] op_sel_hi:[1,0,1]
	v_pk_fma_f32 v[46:47], v[194:195], v[200:201], v[46:47] op_sel_hi:[1,0,1]
	v_pk_fma_f32 v[28:29], v[196:197], v[200:201], v[28:29] op_sel_hi:[1,0,1]
	v_pk_fma_f32 v[30:31], v[198:199], v[200:201], v[30:31] op_sel_hi:[1,0,1]
	v_pk_fma_f32 v[16:17], v[192:193], v[200:201], v[16:17] op_sel:[0,1,0]
	v_pk_fma_f32 v[18:19], v[194:195], v[200:201], v[18:19] op_sel:[0,1,0]
	v_pk_fma_f32 v[8:9], v[196:197], v[200:201], v[8:9] op_sel:[0,1,0]
	v_pk_fma_f32 v[10:11], v[198:199], v[200:201], v[10:11] op_sel:[0,1,0]
	v_pk_fma_f32 v[4:5], v[192:193], v[202:203], v[4:5] op_sel_hi:[1,0,1]
	v_pk_fma_f32 v[6:7], v[194:195], v[202:203], v[6:7] op_sel_hi:[1,0,1]
	v_pk_fma_f32 v[0:1], v[196:197], v[202:203], v[0:1] op_sel_hi:[1,0,1]
	v_pk_fma_f32 v[2:3], v[198:199], v[202:203], v[2:3] op_sel_hi:[1,0,1]
	v_pk_fma_f32 v[52:53], v[192:193], v[204:205], v[52:53] op_sel_hi:[1,0,1]
	v_pk_fma_f32 v[54:55], v[194:195], v[204:205], v[54:55] op_sel_hi:[1,0,1]
	v_pk_fma_f32 v[48:49], v[196:197], v[204:205], v[48:49] op_sel_hi:[1,0,1]
	v_pk_fma_f32 v[50:51], v[198:199], v[204:205], v[50:51] op_sel_hi:[1,0,1]
	v_pk_fma_f32 v[40:41], v[192:193], v[204:205], v[40:41] op_sel:[0,1,0]
	v_pk_fma_f32 v[42:43], v[194:195], v[204:205], v[42:43] op_sel:[0,1,0]
	v_pk_fma_f32 v[36:37], v[196:197], v[204:205], v[36:37] op_sel:[0,1,0]
	v_pk_fma_f32 v[38:39], v[198:199], v[204:205], v[38:39] op_sel:[0,1,0]
	v_pk_fma_f32 v[32:33], v[192:193], v[206:207], v[32:33] op_sel_hi:[1,0,1]
	v_pk_fma_f32 v[34:35], v[194:195], v[206:207], v[34:35] op_sel_hi:[1,0,1]
	v_pk_fma_f32 v[24:25], v[196:197], v[206:207], v[24:25] op_sel_hi:[1,0,1]
	v_pk_fma_f32 v[26:27], v[198:199], v[206:207], v[26:27] op_sel_hi:[1,0,1]
	v_pk_fma_f32 v[20:21], v[192:193], v[144:145], v[20:21] op_sel_hi:[1,0,1]
	v_pk_fma_f32 v[22:23], v[194:195], v[144:145], v[22:23] op_sel_hi:[1,0,1]
	v_pk_fma_f32 v[12:13], v[196:197], v[144:145], v[12:13] op_sel_hi:[1,0,1]
	v_pk_fma_f32 v[14:15], v[198:199], v[144:145], v[14:15] op_sel_hi:[1,0,1]
	s_cbranch_scc0 .LBB0_835
	ds_read_b128 v[152:155], v92 offset:1792
	ds_read_b128 v[156:159], v92 offset:1808
	s_waitcnt lgkmcnt(0)
	v_pk_mul_f32 v[44:45], v[44:45], v[152:153]
	v_pk_mul_f32 v[46:47], v[46:47], v[154:155]
	v_pk_mul_f32 v[28:29], v[28:29], v[156:157]
	v_pk_mul_f32 v[30:31], v[30:31], v[158:159]
	v_pk_mul_f32 v[16:17], v[16:17], v[152:153]
	v_pk_mul_f32 v[18:19], v[18:19], v[154:155]
	v_pk_mul_f32 v[8:9], v[8:9], v[156:157]
	v_pk_mul_f32 v[10:11], v[10:11], v[158:159]
	v_pk_mul_f32 v[60:61], v[60:61], v[152:153]
	v_pk_mul_f32 v[4:5], v[4:5], v[152:153]
	v_pk_mul_f32 v[6:7], v[6:7], v[154:155]
	v_pk_mul_f32 v[62:63], v[62:63], v[154:155]
	v_pk_mul_f32 v[0:1], v[0:1], v[156:157]
	v_pk_mul_f32 v[56:57], v[56:57], v[156:157]
	v_pk_mul_f32 v[2:3], v[2:3], v[158:159]
	v_pk_mul_f32 v[58:59], v[58:59], v[158:159]
	v_pk_mul_f32 v[52:53], v[52:53], v[152:153]
	v_pk_mul_f32 v[54:55], v[54:55], v[154:155]
	v_pk_mul_f32 v[48:49], v[48:49], v[156:157]
	v_pk_mul_f32 v[50:51], v[50:51], v[158:159]
	v_pk_mul_f32 v[20:21], v[20:21], v[152:153]
	v_pk_mul_f32 v[40:41], v[40:41], v[152:153]
	v_pk_mul_f32 v[42:43], v[42:43], v[154:155]
	v_pk_mul_f32 v[22:23], v[22:23], v[154:155]
	v_pk_mul_f32 v[36:37], v[36:37], v[156:157]
	v_pk_mul_f32 v[38:39], v[38:39], v[158:159]
	v_pk_mul_f32 v[12:13], v[12:13], v[156:157]
	v_pk_mul_f32 v[32:33], v[32:33], v[152:153]
	v_pk_mul_f32 v[34:35], v[34:35], v[154:155]
	v_pk_mul_f32 v[14:15], v[14:15], v[158:159]
	v_pk_mul_f32 v[24:25], v[24:25], v[156:157]
	v_pk_mul_f32 v[26:27], v[26:27], v[158:159]
	s_cmp_eq_u32 s21, 32
	s_cbranch_scc0 .LBB0_832
	s_add_i32 s10, s14, s13
	s_ashr_i32 s11, s10, 31
	s_lshl_b64 s[10:11], s[10:11], 15
	v_lshl_add_u64 v[86:87], v[82:83], 0, s[10:11]
	global_store_dwordx4 v[86:87], v[44:47], off
	global_store_dwordx4 v[86:87], v[28:31], off offset:16
	global_store_dwordx4 v[86:87], v[16:19], off offset:256
	global_store_dwordx4 v[86:87], v[8:11], off offset:272
	global_store_dwordx4 v[86:87], v[4:7], off offset:512
	global_store_dwordx4 v[86:87], v[0:3], off offset:528
	global_store_dwordx4 v[86:87], v[60:63], off offset:768
	global_store_dwordx4 v[86:87], v[56:59], off offset:784
	global_store_dwordx4 v[86:87], v[52:55], off offset:1024
	global_store_dwordx4 v[86:87], v[48:51], off offset:1040
	global_store_dwordx4 v[86:87], v[40:43], off offset:1280
	global_store_dwordx4 v[86:87], v[36:39], off offset:1296
	global_store_dwordx4 v[86:87], v[32:35], off offset:1536
	global_store_dwordx4 v[86:87], v[24:27], off offset:1552
	global_store_dwordx4 v[86:87], v[20:23], off offset:1792
	global_store_dwordx4 v[86:87], v[12:15], off offset:1808
	s_branch .LBB0_829

; template <int MODE>
; __device__ __forceinline__ void scan_unit(const Params& p, int l, int chain, int chunk, float* wl) {
;     ...
;     asm volatile("s_waitcnt lgkmcnt(0)" ::: "memory");
; #pragma unroll
;     for (int s = 0; s < TS; ++s) {
;       float e = (float)pe[s], kk = (float)pkk[s], a = (float)pa[s];
;       lw[s * 64 + lane] = __expf(-e);
;       lkk[s * 64 + lane] = kk;
;       lbb[s * 64 + lane] = kk * a;
;       if (MODE >= 1) {
;         lkd[s * 64 + lane] = (float)pk[s] * (1.0f + (a - 1.0f) * ka);
;         lv[s * 64 + lane] = (float)pv[s];
;       }
;       if (MODE == 2) lr[s * 64 + lane] = (float)pr[s];
;     }
;     asm volatile("s_waitcnt lgkmcnt(0)" ::: "memory");
.LBB0_840:
	s_waitcnt lgkmcnt(0)
	s_waitcnt vmcnt(21)
	v_cvt_f32_f16_e32 v246, v103
	v_mov_b32_e32 v244, v246
	v_mul_f32_e32 v247, 0xbfb8aa3b, v244
	v_cvt_f32_f16_e32 v250, v104
	v_exp_f32_e32 v248, v247
	v_cvt_f32_f16_e32 v251, v105
	v_exp_f32_e64 v249, -v247
	ds_write_b32 v91, v250 offset:4096
	v_mul_f32_e32 v253, v250, v251
	v_mul_f32_e32 v253, v253, v249
	ds_write_b32 v91, v253 offset:6144
	ds_write_b32 v91, v248 offset:0
	v_mov_b32_e32 v245, v248
	s_waitcnt vmcnt(18)
	v_cvt_f32_f16_e32 v246, v106
	v_add_f32_e32 v244, v244, v246
	v_mul_f32_e32 v247, 0xbfb8aa3b, v244
	v_cvt_f32_f16_e32 v250, v107
	v_exp_f32_e32 v248, v247
	v_cvt_f32_f16_e32 v251, v108
	v_exp_f32_e64 v249, -v247
	v_mul_f32_e32 v255, v250, v245
	ds_write_b32 v91, v255 offset:4352
	v_mul_f32_e32 v253, v250, v251
	v_mul_f32_e32 v253, v253, v249
	ds_write_b32 v91, v253 offset:6400
	ds_write_b32 v91, v248 offset:256
	v_mov_b32_e32 v245, v248
	s_waitcnt vmcnt(15)
	v_cvt_f32_f16_e32 v246, v109
	v_add_f32_e32 v244, v244, v246
	v_mul_f32_e32 v247, 0xbfb8aa3b, v244
	v_cvt_f32_f16_e32 v250, v110
	v_exp_f32_e32 v248, v247
	v_cvt_f32_f16_e32 v251, v111
	v_exp_f32_e64 v249, -v247
	v_mul_f32_e32 v255, v250, v245
	ds_write_b32 v91, v255 offset:4608
	v_mul_f32_e32 v253, v250, v251
	v_mul_f32_e32 v253, v253, v249
	ds_write_b32 v91, v253 offset:6656
	ds_write_b32 v91, v248 offset:512
	v_mov_b32_e32 v245, v248
	s_waitcnt vmcnt(12)
	v_cvt_f32_f16_e32 v246, v112
	v_add_f32_e32 v244, v244, v246
	v_mul_f32_e32 v247, 0xbfb8aa3b, v244
	v_cvt_f32_f16_e32 v250, v113
	v_exp_f32_e32 v248, v247
	v_cvt_f32_f16_e32 v251, v114
	v_exp_f32_e64 v249, -v247
	v_mul_f32_e32 v255, v250, v245
	ds_write_b32 v91, v255 offset:4864
	v_mul_f32_e32 v253, v250, v251
	v_mul_f32_e32 v253, v253, v249
	ds_write_b32 v91, v253 offset:6912
	ds_write_b32 v91, v248 offset:768
	v_mov_b32_e32 v245, v248
	s_waitcnt vmcnt(9)
	v_cvt_f32_f16_e32 v246, v115
	v_add_f32_e32 v244, v244, v246
	v_mul_f32_e32 v247, 0xbfb8aa3b, v244
	v_cvt_f32_f16_e32 v250, v116
	v_exp_f32_e32 v248, v247
	v_cvt_f32_f16_e32 v251, v117
	v_exp_f32_e64 v249, -v247
	v_mul_f32_e32 v255, v250, v245
	ds_write_b32 v91, v255 offset:5120
	v_mul_f32_e32 v253, v250, v251
	v_mul_f32_e32 v253, v253, v249
	ds_write_b32 v91, v253 offset:7168
	ds_write_b32 v91, v248 offset:1024
	v_mov_b32_e32 v245, v248
	s_waitcnt vmcnt(6)
	v_cvt_f32_f16_e32 v246, v118
	v_add_f32_e32 v244, v244, v246
	v_mul_f32_e32 v247, 0xbfb8aa3b, v244
	v_cvt_f32_f16_e32 v250, v119
	v_exp_f32_e32 v248, v247
	v_cvt_f32_f16_e32 v251, v120
	v_exp_f32_e64 v249, -v247
	v_mul_f32_e32 v255, v250, v245
	ds_write_b32 v91, v255 offset:5376
	v_mul_f32_e32 v253, v250, v251
	v_mul_f32_e32 v253, v253, v249
	ds_write_b32 v91, v253 offset:7424
	ds_write_b32 v91, v248 offset:1280
	v_mov_b32_e32 v245, v248
	s_waitcnt vmcnt(3)
	v_cvt_f32_f16_e32 v246, v121
	v_add_f32_e32 v244, v244, v246
	v_mul_f32_e32 v247, 0xbfb8aa3b, v244
	v_cvt_f32_f16_e32 v250, v122
	v_exp_f32_e32 v248, v247
	v_cvt_f32_f16_e32 v251, v123
	v_exp_f32_e64 v249, -v247
	v_mul_f32_e32 v255, v250, v245
	ds_write_b32 v91, v255 offset:5632
	v_mul_f32_e32 v253, v250, v251
	v_mul_f32_e32 v253, v253, v249
	ds_write_b32 v91, v253 offset:7680
	ds_write_b32 v91, v248 offset:1536
	v_mov_b32_e32 v245, v248
	s_waitcnt vmcnt(0)
	v_cvt_f32_f16_e32 v246, v124
	v_add_f32_e32 v244, v244, v246
	v_mul_f32_e32 v247, 0xbfb8aa3b, v244
	v_cvt_f32_f16_e32 v250, v125
	v_exp_f32_e32 v248, v247
	v_cvt_f32_f16_e32 v251, v126
	v_exp_f32_e64 v249, -v247
	v_mul_f32_e32 v255, v250, v245
	ds_write_b32 v91, v255 offset:5888
	v_mul_f32_e32 v253, v250, v251
	v_mul_f32_e32 v253, v253, v249
	ds_write_b32 v91, v253 offset:7936
	ds_write_b32 v91, v248 offset:1792
	v_mov_b32_e32 v245, v248
	s_mov_b32 s9, s8
	s_waitcnt lgkmcnt(0)
	s_add_i32 s8, s8, 1
	s_cmp_eq_u32 s9, 31
	s_cbranch_scc1 .LBB0_842
	s_lshl_b32 s9, s8, 3
	s_add_i32 s9, s9, s18
	s_not_b32 s15, s9
	s_add_i32 s15, s16, s15
	s_and_b64 s[20:21], s[10:11], exec
	s_cselect_b32 s15, s9, s15
	s_add_i32 s15, s15, s17
	s_xor_b32 s19, s9, -2
	v_mad_i64_i32 v[104:105], s[20:21], s15, v189, v[84:85]
	s_or_b32 s15, s9, 1
	s_add_i32 s19, s19, s16
	v_lshlrev_b64 v[106:107], 1, v[104:105]
	s_and_b64 s[20:21], s[10:11], exec
	v_lshl_add_u64 v[104:105], v[36:37], 0, v[106:107]
	s_cselect_b32 s15, s15, s19
	global_load_ushort v103, v[104:105], off
	v_lshl_add_u64 v[104:105], v[68:69], 0, v[106:107]
	v_lshl_add_u64 v[106:107], v[38:39], 0, v[106:107]
	s_add_i32 s15, s15, s17
	s_xor_b32 s19, s9, -3
	global_load_ushort v104, v[104:105], off
	s_add_i32 s19, s19, s16
	global_load_ushort v105, v[106:107], off
	v_mad_i64_i32 v[106:107], s[20:21], s15, v189, v[84:85]
	s_or_b32 s15, s9, 2
	s_and_b64 s[20:21], s[10:11], exec
	v_lshlrev_b64 v[108:109], 1, v[106:107]
	s_cselect_b32 s15, s15, s19
	v_lshl_add_u64 v[106:107], v[36:37], 0, v[108:109]
	v_lshl_add_u64 v[110:111], v[68:69], 0, v[108:109]
	s_add_i32 s15, s15, s17
	s_xor_b32 s19, s9, -4
	global_load_ushort v106, v[106:107], off
	s_add_i32 s19, s19, s16
	global_load_ushort v107, v[110:111], off
	v_mad_i64_i32 v[110:111], s[20:21], s15, v189, v[84:85]
	s_or_b32 s15, s9, 3
	v_lshlrev_b64 v[112:113], 1, v[110:111]
	s_and_b64 s[20:21], s[10:11], exec
	v_lshl_add_u64 v[108:109], v[38:39], 0, v[108:109]
	v_lshl_add_u64 v[110:111], v[36:37], 0, v[112:113]
	s_cselect_b32 s15, s15, s19
	global_load_ushort v108, v[108:109], off
	s_add_i32 s15, s15, s17
	global_load_ushort v109, v[110:111], off
	v_lshl_add_u64 v[110:111], v[68:69], 0, v[112:113]
	v_lshl_add_u64 v[112:113], v[38:39], 0, v[112:113]
	s_xor_b32 s19, s9, -5
	global_load_ushort v110, v[110:111], off
	s_add_i32 s19, s19, s16
	global_load_ushort v111, v[112:113], off
	v_mad_i64_i32 v[112:113], s[20:21], s15, v189, v[84:85]
	s_or_b32 s15, s9, 4
	s_and_b64 s[20:21], s[10:11], exec
	v_lshlrev_b64 v[114:115], 1, v[112:113]
	s_cselect_b32 s15, s15, s19
	v_lshl_add_u64 v[112:113], v[36:37], 0, v[114:115]
	v_lshl_add_u64 v[116:117], v[68:69], 0, v[114:115]
	s_add_i32 s15, s15, s17
	s_xor_b32 s19, s9, -6
	global_load_ushort v112, v[112:113], off
	s_add_i32 s19, s19, s16
	global_load_ushort v113, v[116:117], off
	v_mad_i64_i32 v[116:117], s[20:21], s15, v189, v[84:85]
	s_or_b32 s15, s9, 5
	v_lshlrev_b64 v[118:119], 1, v[116:117]
	s_and_b64 s[20:21], s[10:11], exec
	v_lshl_add_u64 v[114:115], v[38:39], 0, v[114:115]
	v_lshl_add_u64 v[116:117], v[36:37], 0, v[118:119]
	s_cselect_b32 s15, s15, s19
	global_load_ushort v114, v[114:115], off
	s_add_i32 s15, s15, s17
	global_load_ushort v115, v[116:117], off
	v_lshl_add_u64 v[116:117], v[68:69], 0, v[118:119]
	v_lshl_add_u64 v[118:119], v[38:39], 0, v[118:119]
	s_xor_b32 s19, s9, -7
	global_load_ushort v116, v[116:117], off
	s_add_i32 s19, s19, s16
	global_load_ushort v117, v[118:119], off
	v_mad_i64_i32 v[118:119], s[20:21], s15, v189, v[84:85]
	s_or_b32 s15, s9, 6
	s_and_b64 s[20:21], s[10:11], exec
	v_lshlrev_b64 v[120:121], 1, v[118:119]
	s_cselect_b32 s15, s15, s19
	v_lshl_add_u64 v[118:119], v[36:37], 0, v[120:121]
	v_lshl_add_u64 v[122:123], v[68:69], 0, v[120:121]
	s_add_i32 s15, s15, s17
	global_load_ushort v118, v[118:119], off
	v_lshl_add_u64 v[120:121], v[38:39], 0, v[120:121]
	global_load_ushort v119, v[122:123], off
	v_mad_i64_i32 v[122:123], s[20:21], s15, v189, v[84:85]
	s_or_b32 s15, s9, 7
	s_xor_b32 s9, s9, -8
	s_add_i32 s9, s9, s16
	v_lshlrev_b64 v[124:125], 1, v[122:123]
	s_and_b64 s[20:21], s[10:11], exec
	v_lshl_add_u64 v[122:123], v[36:37], 0, v[124:125]
	s_cselect_b32 s9, s15, s9
	global_load_ushort v120, v[120:121], off
	s_add_i32 s9, s9, s17
	global_load_ushort v121, v[122:123], off
	v_lshl_add_u64 v[122:123], v[68:69], 0, v[124:125]
	v_lshl_add_u64 v[124:125], v[38:39], 0, v[124:125]
	global_load_ushort v122, v[122:123], off
	s_nop 0
	global_load_ushort v123, v[124:125], off
	v_mad_i64_i32 v[124:125], s[20:21], s9, v189, v[84:85]
	v_lshlrev_b64 v[126:127], 1, v[124:125]
	v_lshl_add_u64 v[124:125], v[36:37], 0, v[126:127]
	v_lshl_add_u64 v[128:129], v[68:69], 0, v[126:127]
	v_lshl_add_u64 v[126:127], v[38:39], 0, v[126:127]
	global_load_ushort v124, v[124:125], off
	s_nop 0
	global_load_ushort v125, v[128:129], off
	s_nop 0
	global_load_ushort v126, v[126:127], off

; template <int MODE>
; __device__ __forceinline__ void scan_unit(const Params& p, int l, int chain, int chunk, float* wl) {
;     ...
;     for (int s = 0; s < TS; ++s) {
;       f32x2 kk2[4], w2[4], b2[4], k2[4], r2[4];
;       float v8[8];
;       ld8(lkk + s * 64 + 8 * cj, kk2);
;       ld8(lw + s * 64 + 8 * cj, w2);
;       ld8(lbb + s * 64 + 8 * cj, b2);
;       if (MODE >= 1) {
;         ld8(lkd + s * 64 + 8 * cj, k2);
;         float4 t0 = *(const float4*)(lv + s * 64 + 8 * ri), t1 = *(const float4*)(lv + s * 64 + 8 * ri + 4);
;         v8[0] = t0.x; v8[1] = t0.y; v8[2] = t0.z; v8[3] = t0.w; v8[4] = t1.x; v8[5] = t1.y; v8[6] = t1.z; v8[7] = t1.w;
;       }
;       if (MODE == 2) ld8(lr + s * 64 + 8 * cj, r2);
;       float t[8];
; #pragma unroll
;       for (int a = 0; a < 8; ++a) {
;         f32x2 acc = S[a][0] * kk2[0];
;         acc = S[a][1] * kk2[1] + acc;
;         acc = S[a][2] * kk2[2] + acc;
;         acc = S[a][3] * kk2[3] + acc;
;         t[a] = acc.x + acc.y;
;       }
;       red8x8(t);
;       float yp[8];
; #pragma unroll
;       for (int a = 0; a < 8; ++a) {
;         const float ns = -t[a];
;         const f32x2 ns2 = f32x2{ns, ns};
;         f32x2 ya = f32x2{0.f, 0.f};
; #pragma unroll
;         for (int q = 0; q < 4; ++q) {
;           f32x2 sn = S[a][q] * w2[q] + ns2 * b2[q];
;           if (MODE >= 1) sn = f32x2{v8[a], v8[a]} * k2[q] + sn;
;           S[a][q] = sn;
;           if (MODE == 2) ya = sn * r2[q] + ya;
;         }
;         yp[a] = ya.x + ya.y;
;       }
.LBB0_843:
	v_add_u32_e32 v127, s9, v92
	ds_read_b128 v[128:131], v127 offset:4096
	ds_read_b128 v[132:135], v127 offset:4112
	ds_read_b128 v[136:139], v127
	ds_read_b128 v[140:143], v127 offset:16
	ds_read_b128 v[144:147], v127 offset:6144
	ds_read_b128 v[148:151], v127 offset:6160
	s_waitcnt lgkmcnt(5)
	v_pk_mul_f32 v[152:153], v[62:63], v[130:131]
	s_addk_i32 s9, 0x100
	v_pk_fma_f32 v[152:153], v[88:89], v[128:129], v[152:153]
	s_cmpk_eq_i32 s9, 0x800
	s_waitcnt lgkmcnt(4)
	v_pk_fma_f32 v[152:153], v[58:59], v[132:133], v[152:153]
	s_nop 0
	v_pk_fma_f32 v[152:153], v[52:53], v[134:135], v[152:153]
	s_nop 0
	v_add_f32_e32 v127, v152, v153
	v_pk_mul_f32 v[152:153], v[24:25], v[130:131]
	s_nop 0
	v_pk_fma_f32 v[152:153], v[28:29], v[128:129], v[152:153]
	v_add_f32_dpp v127, v127, v127 quad_perm:[1,0,3,2] row_mask:0xf bank_mask:0xf bound_ctrl:1
	v_pk_fma_f32 v[152:153], v[20:21], v[132:133], v[152:153]
	s_nop 0
	v_pk_fma_f32 v[152:153], v[16:17], v[134:135], v[152:153]
	v_add_f32_dpp v127, v127, v127 quad_perm:[2,3,0,1] row_mask:0xf bank_mask:0xf bound_ctrl:1
	v_add_f32_e32 v154, v152, v153
	v_pk_mul_f32 v[152:153], v[60:61], v[130:131]
	s_nop 0
	v_pk_fma_f32 v[152:153], v[86:87], v[128:129], v[152:153]
	s_nop 0
	v_pk_fma_f32 v[152:153], v[54:55], v[132:133], v[152:153]
	s_nop 0
	v_pk_fma_f32 v[152:153], v[48:49], v[134:135], v[152:153]
	s_nop 0
	v_add_f32_e32 v155, v152, v153
	v_pk_mul_f32 v[152:153], v[26:27], v[130:131]
	s_nop 0
	v_pk_fma_f32 v[152:153], v[30:31], v[128:129], v[152:153]
	s_nop 0
	v_pk_fma_f32 v[152:153], v[22:23], v[132:133], v[152:153]
	s_nop 0
	v_pk_fma_f32 v[152:153], v[18:19], v[134:135], v[152:153]
	s_nop 0
	v_add_f32_e32 v156, v152, v153
	v_pk_mul_f32 v[152:153], v[40:41], v[130:131]
	s_nop 0
	v_pk_fma_f32 v[152:153], v[42:43], v[128:129], v[152:153]
	s_nop 0
	v_pk_fma_f32 v[152:153], v[34:35], v[132:133], v[152:153]
	s_nop 0
	v_pk_fma_f32 v[152:153], v[32:33], v[134:135], v[152:153]
	s_nop 0
	v_add_f32_e32 v157, v152, v153
	v_pk_mul_f32 v[152:153], v[8:9], v[130:131]
	s_nop 0
	v_pk_fma_f32 v[152:153], v[12:13], v[128:129], v[152:153]
	s_nop 0
	v_pk_fma_f32 v[152:153], v[4:5], v[132:133], v[152:153]
	s_nop 0
	v_pk_fma_f32 v[152:153], v[0:1], v[134:135], v[152:153]
	s_nop 0
	v_add_f32_e32 v158, v152, v153
	v_pk_mul_f32 v[152:153], v[50:51], v[130:131]
	v_pk_mul_f32 v[130:131], v[10:11], v[130:131]
	v_pk_fma_f32 v[152:153], v[56:57], v[128:129], v[152:153]
	v_pk_fma_f32 v[128:129], v[14:15], v[128:129], v[130:131]
	v_add_f32_dpp v130, v155, v155 quad_perm:[1,0,3,2] row_mask:0xf bank_mask:0xf bound_ctrl:1
	v_pk_fma_f32 v[128:129], v[6:7], v[132:133], v[128:129]
	v_pk_fma_f32 v[152:153], v[46:47], v[132:133], v[152:153]
	v_pk_fma_f32 v[128:129], v[2:3], v[134:135], v[128:129]
	v_add_f32_dpp v131, v156, v156 quad_perm:[1,0,3,2] row_mask:0xf bank_mask:0xf bound_ctrl:1
	v_add_f32_e32 v128, v128, v129
	v_add_f32_dpp v129, v154, v154 quad_perm:[1,0,3,2] row_mask:0xf bank_mask:0xf bound_ctrl:1
	v_pk_fma_f32 v[152:153], v[44:45], v[134:135], v[152:153]
	v_add_f32_dpp v128, v128, v128 quad_perm:[1,0,3,2] row_mask:0xf bank_mask:0xf bound_ctrl:1
	v_add_f32_dpp v129, v129, v129 quad_perm:[2,3,0,1] row_mask:0xf bank_mask:0xf bound_ctrl:1
	v_add_f32_dpp v135, v130, v130 quad_perm:[2,3,0,1] row_mask:0xf bank_mask:0xf bound_ctrl:1
	v_add_f32_dpp v155, v128, v128 quad_perm:[2,3,0,1] row_mask:0xf bank_mask:0xf bound_ctrl:1
	v_add_f32_dpp v128, v127, v127 row_half_mirror row_mask:0xf bank_mask:0xf bound_ctrl:1
	s_waitcnt lgkmcnt(1)
	v_pk_fma_f32 v[88:89], v[144:145], v[128:129], v[88:89] op_sel_hi:[1,0,1] neg_lo:[0,1,0] neg_hi:[0,1,0]
	v_add_f32_dpp v131, v131, v131 quad_perm:[2,3,0,1] row_mask:0xf bank_mask:0xf bound_ctrl:1
	v_pk_fma_f32 v[62:63], v[146:147], v[128:129], v[62:63] op_sel_hi:[1,0,1] neg_lo:[0,1,0] neg_hi:[0,1,0]
	v_add_f32_dpp v130, v129, v129 row_half_mirror row_mask:0xf bank_mask:0xf bound_ctrl:1
	s_waitcnt lgkmcnt(0)
	v_pk_fma_f32 v[58:59], v[148:149], v[128:129], v[58:59] op_sel_hi:[1,0,1] neg_lo:[0,1,0] neg_hi:[0,1,0]
	v_pk_fma_f32 v[52:53], v[150:151], v[128:129], v[52:53] op_sel_hi:[1,0,1] neg_lo:[0,1,0] neg_hi:[0,1,0]
	v_add_f32_e32 v152, v152, v153
	v_pk_fma_f32 v[28:29], v[144:145], v[130:131], v[28:29] op_sel_hi:[1,0,1] neg_lo:[0,1,0] neg_hi:[0,1,0]
	v_add_f32_dpp v132, v157, v157 quad_perm:[1,0,3,2] row_mask:0xf bank_mask:0xf bound_ctrl:1
	v_pk_fma_f32 v[24:25], v[146:147], v[130:131], v[24:25] op_sel_hi:[1,0,1] neg_lo:[0,1,0] neg_hi:[0,1,0]
	v_add_f32_dpp v133, v158, v158 quad_perm:[1,0,3,2] row_mask:0xf bank_mask:0xf bound_ctrl:1
	v_pk_fma_f32 v[20:21], v[148:149], v[130:131], v[20:21] op_sel_hi:[1,0,1] neg_lo:[0,1,0] neg_hi:[0,1,0]
	v_add_f32_dpp v134, v152, v152 quad_perm:[1,0,3,2] row_mask:0xf bank_mask:0xf bound_ctrl:1
	v_add_f32_dpp v152, v132, v132 quad_perm:[2,3,0,1] row_mask:0xf bank_mask:0xf bound_ctrl:1
	v_add_f32_dpp v133, v133, v133 quad_perm:[2,3,0,1] row_mask:0xf bank_mask:0xf bound_ctrl:1
	v_add_f32_dpp v132, v135, v135 row_half_mirror row_mask:0xf bank_mask:0xf bound_ctrl:1
	v_pk_fma_f32 v[16:17], v[150:151], v[130:131], v[16:17] op_sel_hi:[1,0,1] neg_lo:[0,1,0] neg_hi:[0,1,0]
	v_add_f32_dpp v153, v134, v134 quad_perm:[2,3,0,1] row_mask:0xf bank_mask:0xf bound_ctrl:1
	v_pk_fma_f32 v[86:87], v[144:145], v[132:133], v[86:87] op_sel_hi:[1,0,1] neg_lo:[0,1,0] neg_hi:[0,1,0]
	v_add_f32_dpp v134, v131, v131 row_half_mirror row_mask:0xf bank_mask:0xf bound_ctrl:1
	v_pk_fma_f32 v[60:61], v[146:147], v[132:133], v[60:61] op_sel_hi:[1,0,1] neg_lo:[0,1,0] neg_hi:[0,1,0]
	v_add_f32_dpp v152, v152, v152 row_half_mirror row_mask:0xf bank_mask:0xf bound_ctrl:1
; template <int MODE>
; __device__ __forceinline__ void scan_unit(const Params& p, int l, int chain, int chunk, float* wl) {
;     ...
;       for (int a = 0; a < 8; ++a) {
;         f32x2 acc = S[a][0] * kk2[0];
;         acc = S[a][1] * kk2[1] + acc;
;         acc = S[a][2] * kk2[2] + acc;
;         acc = S[a][3] * kk2[3] + acc;
;         t[a] = acc.x + acc.y;
;       }
;       red8x8(t);
;       float yp[8];
; #pragma unroll
;       for (int a = 0; a < 8; ++a) {
;         const float ns = -t[a];
;         const f32x2 ns2 = f32x2{ns, ns};
;         f32x2 ya = f32x2{0.f, 0.f};
; #pragma unroll
;         for (int q = 0; q < 4; ++q) {
;           f32x2 sn = S[a][q] * w2[q] + ns2 * b2[q];
;           if (MODE >= 1) sn = f32x2{v8[a], v8[a]} * k2[q] + sn;
;           S[a][q] = sn;
;           if (MODE == 2) ya = sn * r2[q] + ya;
;         }
;         yp[a] = ya.x + ya.y;
;       }
;     ...
;   if (MODE == 0) {
;     float* dst = PQ + ((size_t)(chain * NCHUNK + chunk) * 2 + 0) * 4096;
; #pragma unroll
;     for (int a = 0; a < 8; ++a) {
; #pragma unroll
;       for (int bb_ = 0; bb_ < 8; ++bb_) {
;         const int lp = 16 * (2 * (ri & 1) + (a >> 2)) + 8 * (cj & 1) + bb_;
;         const int off = lp * 64 + (cj >> 1) * 16 + (ri >> 1) * 4 + (a & 3);
;         dst[off] = (bb_ & 1) ? S[a][bb_ >> 1].y : S[a][bb_ >> 1].x;
;       }
;     }
;   }
	v_pk_fma_f32 v[54:55], v[148:149], v[132:133], v[54:55] op_sel_hi:[1,0,1] neg_lo:[0,1,0] neg_hi:[0,1,0]
	v_add_f32_dpp v154, v133, v133 row_half_mirror row_mask:0xf bank_mask:0xf bound_ctrl:1
	v_pk_fma_f32 v[48:49], v[150:151], v[132:133], v[48:49] op_sel_hi:[1,0,1] neg_lo:[0,1,0] neg_hi:[0,1,0]
	v_add_f32_dpp v156, v153, v153 row_half_mirror row_mask:0xf bank_mask:0xf bound_ctrl:1
	v_pk_fma_f32 v[30:31], v[144:145], v[134:135], v[30:31] op_sel_hi:[1,0,1] neg_lo:[0,1,0] neg_hi:[0,1,0]
	v_add_f32_dpp v158, v155, v155 row_half_mirror row_mask:0xf bank_mask:0xf bound_ctrl:1
	v_pk_fma_f32 v[26:27], v[146:147], v[134:135], v[26:27] op_sel_hi:[1,0,1] neg_lo:[0,1,0] neg_hi:[0,1,0]
	v_pk_fma_f32 v[22:23], v[148:149], v[134:135], v[22:23] op_sel_hi:[1,0,1] neg_lo:[0,1,0] neg_hi:[0,1,0]
	s_nop 0
	v_pk_fma_f32 v[18:19], v[150:151], v[134:135], v[18:19] op_sel_hi:[1,0,1] neg_lo:[0,1,0] neg_hi:[0,1,0]
	s_nop 0
	v_pk_fma_f32 v[42:43], v[144:145], v[152:153], v[42:43] op_sel_hi:[1,0,1] neg_lo:[0,1,0] neg_hi:[0,1,0]
	s_nop 0
	v_pk_fma_f32 v[40:41], v[146:147], v[152:153], v[40:41] op_sel_hi:[1,0,1] neg_lo:[0,1,0] neg_hi:[0,1,0]
	s_nop 0
	v_pk_fma_f32 v[34:35], v[148:149], v[152:153], v[34:35] op_sel_hi:[1,0,1] neg_lo:[0,1,0] neg_hi:[0,1,0]
	s_nop 0
	v_pk_fma_f32 v[32:33], v[150:151], v[152:153], v[32:33] op_sel_hi:[1,0,1] neg_lo:[0,1,0] neg_hi:[0,1,0]
	s_nop 0
	v_pk_fma_f32 v[12:13], v[144:145], v[154:155], v[12:13] op_sel_hi:[1,0,1] neg_lo:[0,1,0] neg_hi:[0,1,0]
	s_nop 0
	v_pk_fma_f32 v[8:9], v[146:147], v[154:155], v[8:9] op_sel_hi:[1,0,1] neg_lo:[0,1,0] neg_hi:[0,1,0]
	s_nop 0
	v_pk_fma_f32 v[4:5], v[148:149], v[154:155], v[4:5] op_sel_hi:[1,0,1] neg_lo:[0,1,0] neg_hi:[0,1,0]
	s_nop 0
	v_pk_fma_f32 v[0:1], v[150:151], v[154:155], v[0:1] op_sel_hi:[1,0,1] neg_lo:[0,1,0] neg_hi:[0,1,0]
	s_nop 0
	v_pk_fma_f32 v[56:57], v[144:145], v[156:157], v[56:57] op_sel_hi:[1,0,1] neg_lo:[0,1,0] neg_hi:[0,1,0]
	s_nop 0
	v_pk_fma_f32 v[50:51], v[146:147], v[156:157], v[50:51] op_sel_hi:[1,0,1] neg_lo:[0,1,0] neg_hi:[0,1,0]
	s_nop 0
	v_pk_fma_f32 v[46:47], v[148:149], v[156:157], v[46:47] op_sel_hi:[1,0,1] neg_lo:[0,1,0] neg_hi:[0,1,0]
	s_nop 0
	v_pk_fma_f32 v[44:45], v[150:151], v[156:157], v[44:45] op_sel_hi:[1,0,1] neg_lo:[0,1,0] neg_hi:[0,1,0]
	s_nop 0
	v_pk_fma_f32 v[14:15], v[144:145], v[158:159], v[14:15] op_sel_hi:[1,0,1] neg_lo:[0,1,0] neg_hi:[0,1,0]
	s_nop 0
	v_pk_fma_f32 v[10:11], v[146:147], v[158:159], v[10:11] op_sel_hi:[1,0,1] neg_lo:[0,1,0] neg_hi:[0,1,0]
	s_nop 0
	v_pk_fma_f32 v[6:7], v[148:149], v[158:159], v[6:7] op_sel_hi:[1,0,1] neg_lo:[0,1,0] neg_hi:[0,1,0]
	s_nop 0
	v_pk_fma_f32 v[2:3], v[150:151], v[158:159], v[2:3] op_sel_hi:[1,0,1] neg_lo:[0,1,0] neg_hi:[0,1,0]
	s_nop 0
	s_cbranch_scc0 .LBB0_843
	ds_read_b128 v[136:139], v92 offset:1792
	ds_read_b128 v[140:143], v92 offset:1808
	s_waitcnt lgkmcnt(0)
	v_pk_mul_f32 v[88:89], v[88:89], v[136:137]
	v_pk_mul_f32 v[62:63], v[62:63], v[138:139]
	v_pk_mul_f32 v[58:59], v[58:59], v[140:141]
	v_pk_mul_f32 v[52:53], v[52:53], v[142:143]
	v_pk_mul_f32 v[28:29], v[28:29], v[136:137]
	v_pk_mul_f32 v[24:25], v[24:25], v[138:139]
	v_pk_mul_f32 v[20:21], v[20:21], v[140:141]
	v_pk_mul_f32 v[16:17], v[16:17], v[142:143]
	v_pk_mul_f32 v[86:87], v[86:87], v[136:137]
	v_pk_mul_f32 v[60:61], v[60:61], v[138:139]
	v_pk_mul_f32 v[54:55], v[54:55], v[140:141]
	v_pk_mul_f32 v[48:49], v[48:49], v[142:143]
	v_pk_mul_f32 v[30:31], v[30:31], v[136:137]
	v_pk_mul_f32 v[26:27], v[26:27], v[138:139]
	v_pk_mul_f32 v[22:23], v[22:23], v[140:141]
	v_pk_mul_f32 v[18:19], v[18:19], v[142:143]
	v_pk_mul_f32 v[42:43], v[42:43], v[136:137]
	v_pk_mul_f32 v[40:41], v[40:41], v[138:139]
	v_pk_mul_f32 v[34:35], v[34:35], v[140:141]
	v_pk_mul_f32 v[32:33], v[32:33], v[142:143]
	v_pk_mul_f32 v[12:13], v[12:13], v[136:137]
	v_pk_mul_f32 v[8:9], v[8:9], v[138:139]
	v_pk_mul_f32 v[4:5], v[4:5], v[140:141]
	v_pk_mul_f32 v[0:1], v[0:1], v[142:143]
	v_pk_mul_f32 v[56:57], v[56:57], v[136:137]
	v_pk_mul_f32 v[50:51], v[50:51], v[138:139]
	v_pk_mul_f32 v[46:47], v[46:47], v[140:141]
	v_pk_mul_f32 v[44:45], v[44:45], v[142:143]
	v_pk_mul_f32 v[14:15], v[14:15], v[136:137]
	v_pk_mul_f32 v[10:11], v[10:11], v[138:139]
	v_pk_mul_f32 v[6:7], v[6:7], v[140:141]
	v_pk_mul_f32 v[2:3], v[2:3], v[142:143]
	s_cmp_eq_u32 s8, 32
	s_cbranch_scc0 .LBB0_840
	s_add_i32 s8, s14, s13
	s_ashr_i32 s9, s8, 31
	s_lshl_b64 s[8:9], s[8:9], 15
	v_lshl_add_u64 v[84:85], v[78:79], 0, s[8:9]
	v_mov_b32_e32 v37, v28
	v_mov_b32_e32 v39, v30
	v_readfirstlane_b32 s8, v84
	v_readfirstlane_b32 s9, v85
	v_mov_b32_e32 v28, v89
	v_mov_b32_e32 v30, v87
	v_mov_b32_e32 v36, v88
	v_mov_b32_e32 v38, v86
	s_nop 0
	global_store_dwordx4 v94, v[28:31], s[8:9] offset:256
	global_store_dwordx4 v94, v[36:39], s[8:9]
	s_nop 0
	v_mov_b32_e32 v29, v24
	v_mov_b32_e32 v31, v26
	v_mov_b32_e32 v24, v63
	v_mov_b32_e32 v26, v61
	global_store_dwordx4 v94, v[24:27], s[8:9] offset:768
	v_mov_b32_e32 v28, v62
	v_mov_b32_e32 v30, v60
	v_mov_b32_e32 v25, v20
	v_mov_b32_e32 v27, v22
	v_mov_b32_e32 v20, v59
	v_mov_b32_e32 v22, v55
	global_store_dwordx4 v94, v[20:23], s[8:9] offset:1280
	v_mov_b32_e32 v24, v58
	v_mov_b32_e32 v26, v54
	v_mov_b32_e32 v21, v16
	v_mov_b32_e32 v23, v18
	v_mov_b32_e32 v16, v53
	v_mov_b32_e32 v18, v49
	v_mov_b32_e32 v20, v52
	v_mov_b32_e32 v22, v48
	global_store_dwordx4 v94, v[16:19], s[8:9] offset:1792
	global_store_dwordx4 v94, v[28:31], s[8:9] offset:512
	global_store_dwordx4 v94, v[24:27], s[8:9] offset:1024
	v_mov_b32_e32 v16, v42
	v_mov_b32_e32 v17, v12
	v_mov_b32_e32 v18, v56
	v_mov_b32_e32 v19, v14
	v_mov_b32_e32 v12, v43
	v_mov_b32_e32 v14, v57
	global_store_dwordx4 v94, v[20:23], s[8:9] offset:1536
	global_store_dwordx4 v95, v[16:19], s[8:9]
	global_store_dwordx4 v96, v[12:15], s[8:9]
	s_nop 1
	v_mov_b32_e32 v12, v40
	v_mov_b32_e32 v13, v8
	v_mov_b32_e32 v14, v50
	v_mov_b32_e32 v15, v10
	v_mov_b32_e32 v8, v41
	v_mov_b32_e32 v10, v51
	global_store_dwordx4 v97, v[12:15], s[8:9]
	global_store_dwordx4 v98, v[8:11], s[8:9]
	s_nop 1
	v_mov_b32_e32 v8, v34
	v_mov_b32_e32 v9, v4
	v_mov_b32_e32 v10, v46
	v_mov_b32_e32 v11, v6
	v_mov_b32_e32 v4, v35
	v_mov_b32_e32 v6, v47
	global_store_dwordx4 v99, v[8:11], s[8:9]
	global_store_dwordx4 v100, v[4:7], s[8:9]
	s_nop 1
	v_mov_b32_e32 v4, v32
	v_mov_b32_e32 v5, v0
	v_mov_b32_e32 v6, v44
	v_mov_b32_e32 v7, v2
	v_mov_b32_e32 v0, v33
	v_mov_b32_e32 v2, v45
	global_store_dwordx4 v101, v[4:7], s[8:9]
	global_store_dwordx4 v102, v[0:3], s[8:9]
	s_branch .LBB0_829

; template <int MODE>
; __device__ __forceinline__ void scan_unit(const Params& p, int l, int chain, int chunk, float* wl) {
;     ...
;     asm volatile("s_waitcnt lgkmcnt(0)" ::: "memory");
; #pragma unroll
;     for (int s = 0; s < TS; ++s) {
;       float e = (float)pe[s], kk = (float)pkk[s], a = (float)pa[s];
;       lw[s * 64 + lane] = __expf(-e);
;       lkk[s * 64 + lane] = kk;
;       lbb[s * 64 + lane] = kk * a;
;       if (MODE >= 1) {
;         lkd[s * 64 + lane] = (float)pk[s] * (1.0f + (a - 1.0f) * ka);
;         lv[s * 64 + lane] = (float)pv[s];
;       }
;       if (MODE == 2) lr[s * 64 + lane] = (float)pr[s];
;     }
;     asm volatile("s_waitcnt lgkmcnt(0)" ::: "memory");
.LBB0_996:
	s_waitcnt lgkmcnt(0)
	s_waitcnt vmcnt(42)
	v_cvt_f32_f16_e32 v246, v95
	v_mov_b32_e32 v244, v246
	v_mul_f32_e32 v247, 0xbfb8aa3b, v244
	v_cvt_f32_f16_e32 v250, v96
	v_exp_f32_e32 v248, v247
	v_cvt_f32_f16_e32 v251, v97
	v_exp_f32_e64 v249, -v247
	v_cvt_f32_f16_e32 v252, v98
	ds_write_b32 v91, v250 offset:4096
	v_mul_f32_e32 v253, v250, v251
	v_add_f32_e32 v251, -1.0, v251
	v_mul_f32_e32 v253, v253, v249
	ds_write_b32 v91, v253 offset:6144
	v_fma_f32 v251, v94, v251, 1.0
	v_cvt_f32_f16_e32 v254, v99
	v_mul_f32_e32 v252, v251, v252
	v_mul_f32_e32 v252, v252, v249
	ds_write_b32 v91, v252 offset:2048
	ds_write_b32 v91, v254 offset:10240
	v_cvt_f32_f16_e32 v246, v100
	v_mul_f32_e32 v246, v246, v248
	ds_write_b32 v91, v246 offset:8192
	ds_write_b32 v91, v248 offset:0
	v_mov_b32_e32 v245, v248
	s_waitcnt vmcnt(36)
	v_cvt_f32_f16_e32 v246, v101
	v_add_f32_e32 v244, v244, v246
	v_mul_f32_e32 v247, 0xbfb8aa3b, v244
	v_cvt_f32_f16_e32 v250, v102
	v_exp_f32_e32 v248, v247
	v_cvt_f32_f16_e32 v251, v103
	v_exp_f32_e64 v249, -v247
	v_cvt_f32_f16_e32 v252, v104
	v_mul_f32_e32 v255, v250, v245
	ds_write_b32 v91, v255 offset:4352
	v_mul_f32_e32 v253, v250, v251
	v_add_f32_e32 v251, -1.0, v251
	v_mul_f32_e32 v253, v253, v249
	ds_write_b32 v91, v253 offset:6400
	v_fma_f32 v251, v94, v251, 1.0
	v_cvt_f32_f16_e32 v254, v105
	v_mul_f32_e32 v252, v251, v252
	v_mul_f32_e32 v252, v252, v249
	ds_write_b32 v91, v252 offset:2304
	ds_write_b32 v91, v254 offset:10496
	v_cvt_f32_f16_e32 v246, v106
	v_mul_f32_e32 v246, v246, v248
	ds_write_b32 v91, v246 offset:8448
	ds_write_b32 v91, v248 offset:256
	v_mov_b32_e32 v245, v248
	s_waitcnt vmcnt(30)
	v_cvt_f32_f16_e32 v246, v107
	v_add_f32_e32 v244, v244, v246
	v_mul_f32_e32 v247, 0xbfb8aa3b, v244
	v_cvt_f32_f16_e32 v250, v108
	v_exp_f32_e32 v248, v247
	v_cvt_f32_f16_e32 v251, v109
	v_exp_f32_e64 v249, -v247
	v_cvt_f32_f16_e32 v252, v110
	v_mul_f32_e32 v255, v250, v245
	ds_write_b32 v91, v255 offset:4608
	v_mul_f32_e32 v253, v250, v251
	v_add_f32_e32 v251, -1.0, v251
	v_mul_f32_e32 v253, v253, v249
	ds_write_b32 v91, v253 offset:6656
	v_fma_f32 v251, v94, v251, 1.0
	v_cvt_f32_f16_e32 v254, v111
	v_mul_f32_e32 v252, v251, v252
	v_mul_f32_e32 v252, v252, v249
	ds_write_b32 v91, v252 offset:2560
	ds_write_b32 v91, v254 offset:10752
	v_cvt_f32_f16_e32 v246, v112
	v_mul_f32_e32 v246, v246, v248
	ds_write_b32 v91, v246 offset:8704
	ds_write_b32 v91, v248 offset:512
	v_mov_b32_e32 v245, v248
	s_waitcnt vmcnt(24)
	v_cvt_f32_f16_e32 v246, v113
	v_add_f32_e32 v244, v244, v246
	v_mul_f32_e32 v247, 0xbfb8aa3b, v244
	v_cvt_f32_f16_e32 v250, v114
	v_exp_f32_e32 v248, v247
	v_cvt_f32_f16_e32 v251, v115
	v_exp_f32_e64 v249, -v247
	v_cvt_f32_f16_e32 v252, v116
	v_mul_f32_e32 v255, v250, v245
	ds_write_b32 v91, v255 offset:4864
	v_mul_f32_e32 v253, v250, v251
	v_add_f32_e32 v251, -1.0, v251
	v_mul_f32_e32 v253, v253, v249
	ds_write_b32 v91, v253 offset:6912
	v_fma_f32 v251, v94, v251, 1.0
	v_cvt_f32_f16_e32 v254, v117
	v_mul_f32_e32 v252, v251, v252
	v_mul_f32_e32 v252, v252, v249
	ds_write_b32 v91, v252 offset:2816
	ds_write_b32 v91, v254 offset:11008
	v_cvt_f32_f16_e32 v246, v118
	v_mul_f32_e32 v246, v246, v248
	ds_write_b32 v91, v246 offset:8960
	ds_write_b32 v91, v248 offset:768
	v_mov_b32_e32 v245, v248
	s_waitcnt vmcnt(18)
	v_cvt_f32_f16_e32 v246, v119
	v_add_f32_e32 v244, v244, v246
	v_mul_f32_e32 v247, 0xbfb8aa3b, v244
	v_cvt_f32_f16_e32 v250, v120
	v_exp_f32_e32 v248, v247
	v_cvt_f32_f16_e32 v251, v121
	v_exp_f32_e64 v249, -v247
	v_cvt_f32_f16_e32 v252, v122
	v_mul_f32_e32 v255, v250, v245
	ds_write_b32 v91, v255 offset:5120
	v_mul_f32_e32 v253, v250, v251
	v_add_f32_e32 v251, -1.0, v251
	v_mul_f32_e32 v253, v253, v249
	ds_write_b32 v91, v253 offset:7168
	v_fma_f32 v251, v94, v251, 1.0
	v_cvt_f32_f16_e32 v254, v123
	v_mul_f32_e32 v252, v251, v252
	v_mul_f32_e32 v252, v252, v249
	ds_write_b32 v91, v252 offset:3072
	ds_write_b32 v91, v254 offset:11264
	v_cvt_f32_f16_e32 v246, v124
	v_mul_f32_e32 v246, v246, v248
	ds_write_b32 v91, v246 offset:9216
	ds_write_b32 v91, v248 offset:1024
	v_mov_b32_e32 v245, v248
	s_waitcnt vmcnt(12)
	v_cvt_f32_f16_e32 v246, v125
	v_add_f32_e32 v244, v244, v246
	v_mul_f32_e32 v247, 0xbfb8aa3b, v244
	v_cvt_f32_f16_e32 v250, v126
	v_exp_f32_e32 v248, v247
	v_cvt_f32_f16_e32 v251, v127
	v_exp_f32_e64 v249, -v247
	v_cvt_f32_f16_e32 v252, v128
	v_mul_f32_e32 v255, v250, v245
	ds_write_b32 v91, v255 offset:5376
	v_mul_f32_e32 v253, v250, v251
	v_add_f32_e32 v251, -1.0, v251
	v_mul_f32_e32 v253, v253, v249
	ds_write_b32 v91, v253 offset:7424
	v_fma_f32 v251, v94, v251, 1.0
	v_cvt_f32_f16_e32 v254, v129
	v_mul_f32_e32 v252, v251, v252
	v_mul_f32_e32 v252, v252, v249
	ds_write_b32 v91, v252 offset:3328
	ds_write_b32 v91, v254 offset:11520
	v_cvt_f32_f16_e32 v246, v130
	v_mul_f32_e32 v246, v246, v248
	ds_write_b32 v91, v246 offset:9472
	ds_write_b32 v91, v248 offset:1280
	v_mov_b32_e32 v245, v248
	s_waitcnt vmcnt(6)
	v_cvt_f32_f16_e32 v246, v131
	v_add_f32_e32 v244, v244, v246
	v_mul_f32_e32 v247, 0xbfb8aa3b, v244
	v_cvt_f32_f16_e32 v250, v132
	v_exp_f32_e32 v248, v247
	v_cvt_f32_f16_e32 v251, v133
	v_exp_f32_e64 v249, -v247
	v_cvt_f32_f16_e32 v252, v134
	v_mul_f32_e32 v255, v250, v245
	ds_write_b32 v91, v255 offset:5632
	v_mul_f32_e32 v253, v250, v251
	v_add_f32_e32 v251, -1.0, v251
	v_mul_f32_e32 v253, v253, v249
	ds_write_b32 v91, v253 offset:7680
	v_fma_f32 v251, v94, v251, 1.0
	v_cvt_f32_f16_e32 v254, v135
	v_mul_f32_e32 v252, v251, v252
	v_mul_f32_e32 v252, v252, v249
	ds_write_b32 v91, v252 offset:3584
	ds_write_b32 v91, v254 offset:11776
	v_cvt_f32_f16_e32 v246, v136
	v_mul_f32_e32 v246, v246, v248
	ds_write_b32 v91, v246 offset:9728
	ds_write_b32 v91, v248 offset:1536
	v_mov_b32_e32 v245, v248
	s_waitcnt vmcnt(0)
	v_cvt_f32_f16_e32 v246, v137
	v_add_f32_e32 v244, v244, v246
	v_mul_f32_e32 v247, 0xbfb8aa3b, v244
	v_cvt_f32_f16_e32 v250, v138
	v_exp_f32_e32 v248, v247
	v_cvt_f32_f16_e32 v251, v139
	v_exp_f32_e64 v249, -v247
	v_cvt_f32_f16_e32 v252, v140
	v_mul_f32_e32 v255, v250, v245
	ds_write_b32 v91, v255 offset:5888
	v_mul_f32_e32 v253, v250, v251
	v_add_f32_e32 v251, -1.0, v251
	v_mul_f32_e32 v253, v253, v249
	ds_write_b32 v91, v253 offset:7936
	v_fma_f32 v251, v94, v251, 1.0
	v_cvt_f32_f16_e32 v254, v141
	v_mul_f32_e32 v252, v251, v252
	v_mul_f32_e32 v252, v252, v249
	ds_write_b32 v91, v252 offset:3840
	ds_write_b32 v91, v254 offset:12032
	v_cvt_f32_f16_e32 v246, v142
	v_mul_f32_e32 v246, v246, v248
	ds_write_b32 v91, v246 offset:9984
	ds_write_b32 v91, v248 offset:1792
	v_mov_b32_e32 v245, v248
	s_waitcnt lgkmcnt(0)
	s_mov_b32 s42, s25
	s_add_i32 s25, s25, 1
	s_cmp_eq_u32 s42, 31
	s_cbranch_scc1 .LBB0_998
	s_lshl_b32 s42, s25, 3
	s_add_i32 s42, s42, s40
	s_not_b32 s44, s42
	s_add_i32 s46, s24, s44
	s_and_b64 s[44:45], vcc, exec
	s_cselect_b32 s44, s42, s46
	s_add_i32 s44, s44, s38
	v_mad_i64_i32 v[96:97], s[44:45], s44, v189, v[82:83]
	s_xor_b32 s44, s42, -2
	v_lshlrev_b64 v[100:101], 1, v[96:97]
	s_or_b32 s46, s42, 1
	s_add_i32 s47, s44, s24
	v_lshl_add_u64 v[96:97], v[84:85], 0, v[100:101]
	s_and_b64 s[44:45], vcc, exec
	global_load_ushort v95, v[96:97], off
	v_lshl_add_u64 v[96:97], v[70:71], 0, v[100:101]
	v_lshl_add_u64 v[98:99], v[86:87], 0, v[100:101]
	s_cselect_b32 s44, s46, s47
	global_load_ushort v96, v[96:97], off
	v_lshl_add_u64 v[102:103], v[68:69], 0, v[100:101]
	global_load_ushort v97, v[98:99], off
	v_lshl_add_u64 v[98:99], v[66:67], 0, v[100:101]
	s_add_i32 s44, s44, s38
	global_load_ushort v98, v[98:99], off
	s_or_b32 s46, s42, 2
	global_load_ushort v99, v[102:103], off
	v_mad_i64_i32 v[102:103], s[44:45], s44, v189, v[82:83]
	s_xor_b32 s44, s42, -3
	v_lshlrev_b64 v[106:107], 1, v[102:103]
	s_add_i32 s47, s44, s24
	v_lshl_add_u64 v[100:101], v[64:65], 0, v[100:101]
	v_lshl_add_u64 v[102:103], v[84:85], 0, v[106:107]
	s_and_b64 s[44:45], vcc, exec
	global_load_ushort v100, v[100:101], off
	v_lshl_add_u64 v[104:105], v[86:87], 0, v[106:107]
	global_load_ushort v101, v[102:103], off
	v_lshl_add_u64 v[102:103], v[70:71], 0, v[106:107]
	s_cselect_b32 s44, s46, s47
	global_load_ushort v102, v[102:103], off
	v_lshl_add_u64 v[108:109], v[68:69], 0, v[106:107]
	global_load_ushort v103, v[104:105], off
	v_lshl_add_u64 v[104:105], v[66:67], 0, v[106:107]
	s_add_i32 s44, s44, s38
	global_load_ushort v104, v[104:105], off
	s_or_b32 s46, s42, 3
	global_load_ushort v105, v[108:109], off
	v_mad_i64_i32 v[108:109], s[44:45], s44, v189, v[82:83]
	s_xor_b32 s44, s42, -4
	v_lshlrev_b64 v[112:113], 1, v[108:109]
	s_add_i32 s47, s44, s24
	v_lshl_add_u64 v[106:107], v[64:65], 0, v[106:107]
	v_lshl_add_u64 v[108:109], v[84:85], 0, v[112:113]
	s_and_b64 s[44:45], vcc, exec
	global_load_ushort v106, v[106:107], off
	v_lshl_add_u64 v[110:111], v[86:87], 0, v[112:113]
	global_load_ushort v107, v[108:109], off
	v_lshl_add_u64 v[108:109], v[70:71], 0, v[112:113]
	s_cselect_b32 s44, s46, s47
	global_load_ushort v108, v[108:109], off
	v_lshl_add_u64 v[114:115], v[68:69], 0, v[112:113]
	global_load_ushort v109, v[110:111], off
	v_lshl_add_u64 v[110:111], v[66:67], 0, v[112:113]
	s_add_i32 s44, s44, s38
	global_load_ushort v110, v[110:111], off
	s_or_b32 s46, s42, 4
	global_load_ushort v111, v[114:115], off
	v_mad_i64_i32 v[114:115], s[44:45], s44, v189, v[82:83]
	s_xor_b32 s44, s42, -5
	v_lshlrev_b64 v[118:119], 1, v[114:115]
	s_add_i32 s47, s44, s24
	v_lshl_add_u64 v[112:113], v[64:65], 0, v[112:113]
	v_lshl_add_u64 v[114:115], v[84:85], 0, v[118:119]
	s_and_b64 s[44:45], vcc, exec
	global_load_ushort v112, v[112:113], off
	v_lshl_add_u64 v[116:117], v[86:87], 0, v[118:119]
	global_load_ushort v113, v[114:115], off
	v_lshl_add_u64 v[114:115], v[70:71], 0, v[118:119]
	s_cselect_b32 s44, s46, s47
	global_load_ushort v114, v[114:115], off
	v_lshl_add_u64 v[120:121], v[68:69], 0, v[118:119]
	global_load_ushort v115, v[116:117], off
	v_lshl_add_u64 v[116:117], v[66:67], 0, v[118:119]
	s_add_i32 s44, s44, s38
	global_load_ushort v116, v[116:117], off
	s_or_b32 s46, s42, 5
	global_load_ushort v117, v[120:121], off
	v_mad_i64_i32 v[120:121], s[44:45], s44, v189, v[82:83]
	s_xor_b32 s44, s42, -6
	v_lshlrev_b64 v[124:125], 1, v[120:121]
	s_add_i32 s47, s44, s24
	v_lshl_add_u64 v[118:119], v[64:65], 0, v[118:119]
	v_lshl_add_u64 v[120:121], v[84:85], 0, v[124:125]
	s_and_b64 s[44:45], vcc, exec
	global_load_ushort v118, v[118:119], off
	v_lshl_add_u64 v[122:123], v[86:87], 0, v[124:125]
	global_load_ushort v119, v[120:121], off
	v_lshl_add_u64 v[120:121], v[70:71], 0, v[124:125]
	s_cselect_b32 s44, s46, s47
	global_load_ushort v120, v[120:121], off
	v_lshl_add_u64 v[126:127], v[68:69], 0, v[124:125]
	global_load_ushort v121, v[122:123], off
	v_lshl_add_u64 v[122:123], v[66:67], 0, v[124:125]
	s_add_i32 s44, s44, s38
	global_load_ushort v122, v[122:123], off
	s_or_b32 s46, s42, 6
	global_load_ushort v123, v[126:127], off
	v_mad_i64_i32 v[126:127], s[44:45], s44, v189, v[82:83]
	s_xor_b32 s44, s42, -7
	v_lshlrev_b64 v[130:131], 1, v[126:127]
	s_add_i32 s47, s44, s24
	v_lshl_add_u64 v[124:125], v[64:65], 0, v[124:125]
	v_lshl_add_u64 v[126:127], v[84:85], 0, v[130:131]
	s_and_b64 s[44:45], vcc, exec
	global_load_ushort v124, v[124:125], off
	v_lshl_add_u64 v[128:129], v[86:87], 0, v[130:131]
	global_load_ushort v125, v[126:127], off
	v_lshl_add_u64 v[126:127], v[70:71], 0, v[130:131]
	s_cselect_b32 s44, s46, s47
	global_load_ushort v126, v[126:127], off
	v_lshl_add_u64 v[132:133], v[68:69], 0, v[130:131]
	global_load_ushort v127, v[128:129], off
	v_lshl_add_u64 v[128:129], v[66:67], 0, v[130:131]
	s_add_i32 s44, s44, s38
	global_load_ushort v128, v[128:129], off
	s_or_b32 s46, s42, 7
	global_load_ushort v129, v[132:133], off
	v_mad_i64_i32 v[132:133], s[44:45], s44, v189, v[82:83]
	s_xor_b32 s42, s42, -8
	v_lshlrev_b64 v[136:137], 1, v[132:133]
	s_add_i32 s42, s42, s24
	v_lshl_add_u64 v[130:131], v[64:65], 0, v[130:131]
	v_lshl_add_u64 v[132:133], v[84:85], 0, v[136:137]
	s_and_b64 s[44:45], vcc, exec
	global_load_ushort v130, v[130:131], off
	v_lshl_add_u64 v[134:135], v[86:87], 0, v[136:137]
	global_load_ushort v131, v[132:133], off
	v_lshl_add_u64 v[132:133], v[70:71], 0, v[136:137]
	s_cselect_b32 s42, s46, s42
	global_load_ushort v132, v[132:133], off
	v_lshl_add_u64 v[138:139], v[68:69], 0, v[136:137]
	global_load_ushort v133, v[134:135], off
	v_lshl_add_u64 v[134:135], v[66:67], 0, v[136:137]
	s_add_i32 s42, s42, s38
	global_load_ushort v134, v[134:135], off
	v_lshl_add_u64 v[136:137], v[64:65], 0, v[136:137]
	global_load_ushort v135, v[138:139], off
	v_mad_i64_i32 v[138:139], s[44:45], s42, v189, v[82:83]
	v_lshlrev_b64 v[142:143], 1, v[138:139]
	v_lshl_add_u64 v[138:139], v[84:85], 0, v[142:143]
	global_load_ushort v136, v[136:137], off
	v_lshl_add_u64 v[140:141], v[86:87], 0, v[142:143]
	global_load_ushort v137, v[138:139], off
	v_lshl_add_u64 v[138:139], v[70:71], 0, v[142:143]
	global_load_ushort v138, v[138:139], off
	v_lshl_add_u64 v[144:145], v[68:69], 0, v[142:143]
	global_load_ushort v139, v[140:141], off
	v_lshl_add_u64 v[140:141], v[66:67], 0, v[142:143]
	v_lshl_add_u64 v[142:143], v[64:65], 0, v[142:143]
	global_load_ushort v140, v[140:141], off
	s_nop 0
	global_load_ushort v141, v[144:145], off
	s_nop 0
	global_load_ushort v142, v[142:143], off

; template <int MODE>
; __device__ __forceinline__ void scan_unit(const Params& p, int l, int chain, int chunk, float* wl) {
;     ...
;     for (int s = 0; s < TS; ++s) {
;       f32x2 kk2[4], w2[4], b2[4], k2[4], r2[4];
;       float v8[8];
;       ld8(lkk + s * 64 + 8 * cj, kk2);
;       ld8(lw + s * 64 + 8 * cj, w2);
;       ld8(lbb + s * 64 + 8 * cj, b2);
;       if (MODE >= 1) {
;         ld8(lkd + s * 64 + 8 * cj, k2);
;         float4 t0 = *(const float4*)(lv + s * 64 + 8 * ri), t1 = *(const float4*)(lv + s * 64 + 8 * ri + 4);
;         v8[0] = t0.x; v8[1] = t0.y; v8[2] = t0.z; v8[3] = t0.w; v8[4] = t1.x; v8[5] = t1.y; v8[6] = t1.z; v8[7] = t1.w;
;       }
;       if (MODE == 2) ld8(lr + s * 64 + 8 * cj, r2);
;       float t[8];
; #pragma unroll
;       for (int a = 0; a < 8; ++a) {
;         f32x2 acc = S[a][0] * kk2[0];
;         acc = S[a][1] * kk2[1] + acc;
;         acc = S[a][2] * kk2[2] + acc;
;         acc = S[a][3] * kk2[3] + acc;
;         t[a] = acc.x + acc.y;
;       }
;       red8x8(t);
;       float yp[8];
; #pragma unroll
;       for (int a = 0; a < 8; ++a) {
;         const float ns = -t[a];
;         const f32x2 ns2 = f32x2{ns, ns};
;         f32x2 ya = f32x2{0.f, 0.f};
; #pragma unroll
;         for (int q = 0; q < 4; ++q) {
;           f32x2 sn = S[a][q] * w2[q] + ns2 * b2[q];
;           if (MODE >= 1) sn = f32x2{v8[a], v8[a]} * k2[q] + sn;
;           S[a][q] = sn;
;           if (MODE == 2) ya = sn * r2[q] + ya;
;         }
;         yp[a] = ya.x + ya.y;
.LBB0_999:
	v_add_u32_e32 v143, s42, v92
	ds_read_b128 v[144:147], v143 offset:4096
	ds_read_b128 v[148:151], v143 offset:4112
	ds_read_b128 v[152:155], v143
	ds_read_b128 v[156:159], v143 offset:16
	ds_read_b128 v[160:163], v143 offset:6144
	ds_read_b128 v[166:169], v143 offset:6160
	ds_read_b128 v[192:195], v143 offset:2048
	ds_read_b128 v[196:199], v143 offset:2064
	s_waitcnt lgkmcnt(7)
	v_pk_mul_f32 v[216:217], v[6:7], v[146:147]
	v_add_u32_e32 v164, s42, v93
	v_pk_fma_f32 v[216:217], v[4:5], v[144:145], v[216:217]
	ds_read_b128 v[200:203], v164
	ds_read_b128 v[204:207], v164 offset:16
	ds_read_b128 v[208:211], v143 offset:8192
	ds_read_b128 v[212:215], v143 offset:8208
	s_waitcnt lgkmcnt(10)
	v_pk_fma_f32 v[216:217], v[0:1], v[148:149], v[216:217]
	s_and_b64 s[46:47], vcc, exec
	v_pk_fma_f32 v[216:217], v[2:3], v[150:151], v[216:217]
	s_cselect_b32 s46, s45, s44
	v_add_f32_e32 v143, v216, v217
	v_pk_mul_f32 v[216:217], v[14:15], v[146:147]
	s_add_i32 s46, s46, s38
	v_pk_fma_f32 v[216:217], v[12:13], v[144:145], v[216:217]
	v_add_f32_dpp v143, v143, v143 quad_perm:[1,0,3,2] row_mask:0xf bank_mask:0xf bound_ctrl:1
	v_pk_fma_f32 v[216:217], v[8:9], v[148:149], v[216:217]
	s_addk_i32 s42, 0x100
	v_pk_fma_f32 v[216:217], v[10:11], v[150:151], v[216:217]
	v_add_f32_dpp v143, v143, v143 quad_perm:[2,3,0,1] row_mask:0xf bank_mask:0xf bound_ctrl:1
	v_add_f32_e32 v164, v216, v217
	v_pk_mul_f32 v[216:217], v[18:19], v[146:147]
	s_add_i32 s45, s45, 1
	v_pk_fma_f32 v[216:217], v[16:17], v[144:145], v[216:217]
	s_add_i32 s44, s44, -1
	v_pk_fma_f32 v[216:217], v[20:21], v[148:149], v[216:217]
	s_cmpk_eq_i32 s42, 0x800
	v_pk_fma_f32 v[216:217], v[22:23], v[150:151], v[216:217]
	s_nop 0
	v_add_f32_e32 v170, v216, v217
	v_pk_mul_f32 v[216:217], v[26:27], v[146:147]
	s_nop 0
	v_pk_fma_f32 v[216:217], v[24:25], v[144:145], v[216:217]
	s_nop 0
	v_pk_fma_f32 v[216:217], v[28:29], v[148:149], v[216:217]
	s_nop 0
	v_pk_fma_f32 v[216:217], v[30:31], v[150:151], v[216:217]
	s_nop 0
	v_add_f32_e32 v218, v216, v217
	v_pk_mul_f32 v[216:217], v[34:35], v[146:147]
	s_nop 0
	v_pk_fma_f32 v[216:217], v[32:33], v[144:145], v[216:217]
	s_nop 0
	v_pk_fma_f32 v[216:217], v[36:37], v[148:149], v[216:217]
	s_nop 0
	v_pk_fma_f32 v[216:217], v[38:39], v[150:151], v[216:217]
	s_nop 0
	v_add_f32_e32 v219, v216, v217
	v_pk_mul_f32 v[216:217], v[42:43], v[146:147]
	s_nop 0
	v_pk_fma_f32 v[216:217], v[40:41], v[144:145], v[216:217]
	s_nop 0
	v_pk_fma_f32 v[216:217], v[44:45], v[148:149], v[216:217]
	s_nop 0
	v_pk_fma_f32 v[216:217], v[46:47], v[150:151], v[216:217]
	s_nop 0
	v_add_f32_e32 v220, v216, v217
	v_pk_mul_f32 v[216:217], v[50:51], v[146:147]
	v_pk_mul_f32 v[146:147], v[58:59], v[146:147]
	v_pk_fma_f32 v[216:217], v[48:49], v[144:145], v[216:217]
	v_pk_fma_f32 v[144:145], v[56:57], v[144:145], v[146:147]
	v_pk_fma_f32 v[216:217], v[52:53], v[148:149], v[216:217]
	v_pk_fma_f32 v[144:145], v[60:61], v[148:149], v[144:145]
	v_pk_fma_f32 v[216:217], v[54:55], v[150:151], v[216:217]
	v_pk_fma_f32 v[144:145], v[62:63], v[150:151], v[144:145]
	v_add_f32_e32 v216, v216, v217
	v_add_f32_e32 v144, v144, v145
	v_add_f32_dpp v145, v164, v164 quad_perm:[1,0,3,2] row_mask:0xf bank_mask:0xf bound_ctrl:1
	v_add_f32_dpp v149, v220, v220 quad_perm:[1,0,3,2] row_mask:0xf bank_mask:0xf bound_ctrl:1
	v_add_f32_dpp v144, v144, v144 quad_perm:[1,0,3,2] row_mask:0xf bank_mask:0xf bound_ctrl:1
	v_add_f32_dpp v145, v145, v145 quad_perm:[2,3,0,1] row_mask:0xf bank_mask:0xf bound_ctrl:1
	v_add_f32_dpp v146, v170, v170 quad_perm:[1,0,3,2] row_mask:0xf bank_mask:0xf bound_ctrl:1
	v_add_f32_dpp v217, v144, v144 quad_perm:[2,3,0,1] row_mask:0xf bank_mask:0xf bound_ctrl:1
	v_add_f32_dpp v144, v143, v143 row_half_mirror row_mask:0xf bank_mask:0xf bound_ctrl:1
	s_waitcnt lgkmcnt(7)
	v_pk_fma_f32 v[4:5], v[160:161], v[144:145], v[4:5] op_sel_hi:[1,0,1] neg_lo:[0,1,0] neg_hi:[0,1,0]
	v_pk_fma_f32 v[6:7], v[162:163], v[144:145], v[6:7] op_sel_hi:[1,0,1] neg_lo:[0,1,0] neg_hi:[0,1,0]
	s_waitcnt lgkmcnt(3)
	v_pk_fma_f32 v[4:5], v[192:193], v[200:201], v[4:5] op_sel_hi:[1,0,1]
	v_pk_fma_f32 v[0:1], v[166:167], v[144:145], v[0:1] op_sel_hi:[1,0,1] neg_lo:[0,1,0] neg_hi:[0,1,0]
	v_add_f32_dpp v151, v146, v146 quad_perm:[2,3,0,1] row_mask:0xf bank_mask:0xf bound_ctrl:1
	v_add_f32_dpp v146, v145, v145 row_half_mirror row_mask:0xf bank_mask:0xf bound_ctrl:1
	s_waitcnt lgkmcnt(1)
	v_pk_fma_f32 v[220:221], v[208:209], v[4:5], 0 op_sel_hi:[1,1,0]
	v_pk_fma_f32 v[6:7], v[194:195], v[200:201], v[6:7] op_sel_hi:[1,0,1]
	v_pk_fma_f32 v[2:3], v[168:169], v[144:145], v[2:3] op_sel_hi:[1,0,1] neg_lo:[0,1,0] neg_hi:[0,1,0]
	v_pk_fma_f32 v[220:221], v[210:211], v[6:7], v[220:221]
	v_pk_fma_f32 v[0:1], v[196:197], v[200:201], v[0:1] op_sel_hi:[1,0,1]
	v_add_f32_dpp v147, v218, v218 quad_perm:[1,0,3,2] row_mask:0xf bank_mask:0xf bound_ctrl:1
	s_waitcnt lgkmcnt(0)
; template <int MODE>
; __device__ __forceinline__ void scan_unit(const Params& p, int l, int chain, int chunk, float* wl) {
;     ...
;       for (int a = 0; a < 8; ++a) {
;         const float ns = -t[a];
;         const f32x2 ns2 = f32x2{ns, ns};
;         f32x2 ya = f32x2{0.f, 0.f};
; #pragma unroll
;         for (int q = 0; q < 4; ++q) {
;           f32x2 sn = S[a][q] * w2[q] + ns2 * b2[q];
;           if (MODE >= 1) sn = f32x2{v8[a], v8[a]} * k2[q] + sn;
;           S[a][q] = sn;
;           if (MODE == 2) ya = sn * r2[q] + ya;
;         }
;         yp[a] = ya.x + ya.y;
	v_pk_fma_f32 v[220:221], v[212:213], v[0:1], v[220:221]
	v_pk_fma_f32 v[2:3], v[198:199], v[200:201], v[2:3] op_sel_hi:[1,0,1]
	v_add_f32_dpp v147, v147, v147 quad_perm:[2,3,0,1] row_mask:0xf bank_mask:0xf bound_ctrl:1
	v_pk_fma_f32 v[144:145], v[214:215], v[2:3], v[220:221]
	v_pk_fma_f32 v[14:15], v[162:163], v[146:147], v[14:15] op_sel_hi:[1,0,1] neg_lo:[0,1,0] neg_hi:[0,1,0]
	v_add_f32_e32 v143, v144, v145
	v_pk_fma_f32 v[12:13], v[160:161], v[146:147], v[12:13] op_sel_hi:[1,0,1] neg_lo:[0,1,0] neg_hi:[0,1,0]
	v_add_f32_dpp v150, v216, v216 quad_perm:[1,0,3,2] row_mask:0xf bank_mask:0xf bound_ctrl:1
	v_pk_fma_f32 v[12:13], v[192:193], v[200:201], v[12:13] op_sel:[0,1,0]
	v_pk_fma_f32 v[8:9], v[166:167], v[146:147], v[8:9] op_sel_hi:[1,0,1] neg_lo:[0,1,0] neg_hi:[0,1,0]
	v_add_f32_dpp v216, v150, v150 quad_perm:[2,3,0,1] row_mask:0xf bank_mask:0xf bound_ctrl:1
	v_add_f32_dpp v150, v147, v147 row_half_mirror row_mask:0xf bank_mask:0xf bound_ctrl:1
	v_pk_fma_f32 v[144:145], v[208:209], v[12:13], 0 op_sel_hi:[1,1,0]
	v_pk_fma_f32 v[14:15], v[194:195], v[200:201], v[14:15] op_sel:[0,1,0]
	v_pk_fma_f32 v[10:11], v[168:169], v[146:147], v[10:11] op_sel_hi:[1,0,1] neg_lo:[0,1,0] neg_hi:[0,1,0]
	v_pk_fma_f32 v[144:145], v[210:211], v[14:15], v[144:145]
	v_pk_fma_f32 v[8:9], v[196:197], v[200:201], v[8:9] op_sel:[0,1,0]
	v_add_f32_dpp v148, v219, v219 quad_perm:[1,0,3,2] row_mask:0xf bank_mask:0xf bound_ctrl:1
	v_pk_fma_f32 v[144:145], v[212:213], v[8:9], v[144:145]
	v_pk_fma_f32 v[10:11], v[198:199], v[200:201], v[10:11] op_sel:[0,1,0]
	v_add_f32_dpp v164, v148, v148 quad_perm:[2,3,0,1] row_mask:0xf bank_mask:0xf bound_ctrl:1
	v_add_f32_dpp v149, v149, v149 quad_perm:[2,3,0,1] row_mask:0xf bank_mask:0xf bound_ctrl:1
	v_add_f32_dpp v148, v151, v151 row_half_mirror row_mask:0xf bank_mask:0xf bound_ctrl:1
	v_pk_fma_f32 v[144:145], v[214:215], v[10:11], v[144:145]
	v_pk_fma_f32 v[18:19], v[162:163], v[148:149], v[18:19] op_sel_hi:[1,0,1] neg_lo:[0,1,0] neg_hi:[0,1,0]
	v_add_f32_e32 v151, v144, v145
	v_pk_fma_f32 v[16:17], v[160:161], v[148:149], v[16:17] op_sel_hi:[1,0,1] neg_lo:[0,1,0] neg_hi:[0,1,0]
	v_pk_fma_f32 v[20:21], v[166:167], v[148:149], v[20:21] op_sel_hi:[1,0,1] neg_lo:[0,1,0] neg_hi:[0,1,0]
	v_pk_fma_f32 v[16:17], v[192:193], v[202:203], v[16:17] op_sel_hi:[1,0,1]
	v_pk_fma_f32 v[18:19], v[194:195], v[202:203], v[18:19] op_sel_hi:[1,0,1]
	v_pk_fma_f32 v[144:145], v[208:209], v[16:17], 0 op_sel_hi:[1,1,0]
	v_pk_fma_f32 v[22:23], v[168:169], v[148:149], v[22:23] op_sel_hi:[1,0,1] neg_lo:[0,1,0] neg_hi:[0,1,0]
	v_pk_fma_f32 v[144:145], v[210:211], v[18:19], v[144:145]
	v_pk_fma_f32 v[20:21], v[196:197], v[202:203], v[20:21] op_sel_hi:[1,0,1]
	s_nop 0
	v_pk_fma_f32 v[144:145], v[212:213], v[20:21], v[144:145]
	v_pk_fma_f32 v[22:23], v[198:199], v[202:203], v[22:23] op_sel_hi:[1,0,1]
	v_pk_fma_f32 v[24:25], v[160:161], v[150:151], v[24:25] op_sel_hi:[1,0,1] neg_lo:[0,1,0] neg_hi:[0,1,0]
	v_pk_fma_f32 v[144:145], v[214:215], v[22:23], v[144:145]
	v_add_f32_dpp v170, v149, v149 row_half_mirror row_mask:0xf bank_mask:0xf bound_ctrl:1
	v_add_f32_e32 v200, v144, v145
	v_mov_b32_e32 v144, v203
	v_pk_fma_f32 v[26:27], v[162:163], v[150:151], v[26:27] op_sel_hi:[1,0,1] neg_lo:[0,1,0] neg_hi:[0,1,0]
	v_pk_fma_f32 v[24:25], v[192:193], v[144:145], v[24:25] op_sel_hi:[1,0,1]
	v_pk_fma_f32 v[28:29], v[166:167], v[150:151], v[28:29] op_sel_hi:[1,0,1] neg_lo:[0,1,0] neg_hi:[0,1,0]
	v_pk_fma_f32 v[146:147], v[208:209], v[24:25], 0 op_sel_hi:[1,1,0]
	v_pk_fma_f32 v[26:27], v[194:195], v[144:145], v[26:27] op_sel_hi:[1,0,1]
	v_pk_fma_f32 v[30:31], v[168:169], v[150:151], v[30:31] op_sel_hi:[1,0,1] neg_lo:[0,1,0] neg_hi:[0,1,0]
	v_pk_fma_f32 v[146:147], v[210:211], v[26:27], v[146:147]
	v_pk_fma_f32 v[28:29], v[196:197], v[144:145], v[28:29] op_sel_hi:[1,0,1]
	s_nop 0
	v_pk_fma_f32 v[146:147], v[212:213], v[28:29], v[146:147]
	v_pk_fma_f32 v[30:31], v[198:199], v[144:145], v[30:31] op_sel_hi:[1,0,1]
	v_add_f32_dpp v164, v164, v164 row_half_mirror row_mask:0xf bank_mask:0xf bound_ctrl:1
	v_pk_fma_f32 v[144:145], v[214:215], v[30:31], v[146:147]
	v_pk_fma_f32 v[34:35], v[162:163], v[164:165], v[34:35] op_sel_hi:[1,0,1] neg_lo:[0,1,0] neg_hi:[0,1,0]
	v_add_f32_e32 v150, v144, v145
	v_pk_fma_f32 v[32:33], v[160:161], v[164:165], v[32:33] op_sel_hi:[1,0,1] neg_lo:[0,1,0] neg_hi:[0,1,0]
	v_pk_fma_f32 v[36:37], v[166:167], v[164:165], v[36:37] op_sel_hi:[1,0,1] neg_lo:[0,1,0] neg_hi:[0,1,0]
	v_pk_fma_f32 v[32:33], v[192:193], v[204:205], v[32:33] op_sel_hi:[1,0,1]
	v_pk_fma_f32 v[34:35], v[194:195], v[204:205], v[34:35] op_sel_hi:[1,0,1]
	v_pk_fma_f32 v[144:145], v[208:209], v[32:33], 0 op_sel_hi:[1,1,0]
	v_pk_fma_f32 v[38:39], v[168:169], v[164:165], v[38:39] op_sel_hi:[1,0,1] neg_lo:[0,1,0] neg_hi:[0,1,0]
	v_pk_fma_f32 v[144:145], v[210:211], v[34:35], v[144:145]
	v_pk_fma_f32 v[36:37], v[196:197], v[204:205], v[36:37] op_sel_hi:[1,0,1]
	s_nop 0
	v_pk_fma_f32 v[144:145], v[212:213], v[36:37], v[144:145]
	v_pk_fma_f32 v[38:39], v[198:199], v[204:205], v[38:39] op_sel_hi:[1,0,1]
	v_pk_fma_f32 v[42:43], v[162:163], v[170:171], v[42:43] op_sel_hi:[1,0,1] neg_lo:[0,1,0] neg_hi:[0,1,0]
	v_pk_fma_f32 v[144:145], v[214:215], v[38:39], v[144:145]
	s_nop 0
	v_add_f32_e32 v164, v144, v145
	v_pk_fma_f32 v[40:41], v[160:161], v[170:171], v[40:41] op_sel_hi:[1,0,1] neg_lo:[0,1,0] neg_hi:[0,1,0]
	v_pk_fma_f32 v[44:45], v[166:167], v[170:171], v[44:45] op_sel_hi:[1,0,1] neg_lo:[0,1,0] neg_hi:[0,1,0]
	v_pk_fma_f32 v[42:43], v[194:195], v[204:205], v[42:43] op_sel:[0,1,0]
	v_pk_fma_f32 v[40:41], v[192:193], v[204:205], v[40:41] op_sel:[0,1,0]
	s_nop 0
; template <int MODE>
; __device__ __forceinline__ void scan_unit(const Params& p, int l, int chain, int chunk, float* wl) {
;     ...
;       for (int a = 0; a < 8; ++a) {
;         const float ns = -t[a];
;         const f32x2 ns2 = f32x2{ns, ns};
;         f32x2 ya = f32x2{0.f, 0.f};
; #pragma unroll
;         for (int q = 0; q < 4; ++q) {
;           f32x2 sn = S[a][q] * w2[q] + ns2 * b2[q];
;           if (MODE >= 1) sn = f32x2{v8[a], v8[a]} * k2[q] + sn;
;           S[a][q] = sn;
;           if (MODE == 2) ya = sn * r2[q] + ya;
;         }
;         yp[a] = ya.x + ya.y;
;       }
;       float ysel = 0.f;
;       if (MODE == 2) {
;         red8x8(yp);
; #pragma unroll
;         for (int a = 0; a < 8; ++a) ysel = (cj == a) ? yp[a] : ysel;
;       }
;       if (MODE == 2) {
;         int st = st0 + tile * TS + s;
;         int t = z == 0 ? st : len - 1 - st;
;         Y[(size_t)(rowbase + t) * RD + c] = f2bf(ysel);
	v_pk_fma_f32 v[144:145], v[208:209], v[40:41], 0 op_sel_hi:[1,1,0]
	v_pk_fma_f32 v[46:47], v[168:169], v[170:171], v[46:47] op_sel_hi:[1,0,1] neg_lo:[0,1,0] neg_hi:[0,1,0]
	v_pk_fma_f32 v[144:145], v[210:211], v[42:43], v[144:145]
	v_pk_fma_f32 v[44:45], v[196:197], v[204:205], v[44:45] op_sel:[0,1,0]
	s_nop 0
	v_pk_fma_f32 v[144:145], v[212:213], v[44:45], v[144:145]
	v_pk_fma_f32 v[46:47], v[198:199], v[204:205], v[46:47] op_sel:[0,1,0]
	v_add_f32_dpp v216, v216, v216 row_half_mirror row_mask:0xf bank_mask:0xf bound_ctrl:1
	v_pk_fma_f32 v[144:145], v[214:215], v[46:47], v[144:145]
	v_pk_fma_f32 v[50:51], v[162:163], v[216:217], v[50:51] op_sel_hi:[1,0,1] neg_lo:[0,1,0] neg_hi:[0,1,0]
	v_add_f32_e32 v170, v144, v145
	v_pk_fma_f32 v[48:49], v[160:161], v[216:217], v[48:49] op_sel_hi:[1,0,1] neg_lo:[0,1,0] neg_hi:[0,1,0]
	v_pk_fma_f32 v[52:53], v[166:167], v[216:217], v[52:53] op_sel_hi:[1,0,1] neg_lo:[0,1,0] neg_hi:[0,1,0]
	v_pk_fma_f32 v[48:49], v[192:193], v[206:207], v[48:49] op_sel_hi:[1,0,1]
	v_pk_fma_f32 v[50:51], v[194:195], v[206:207], v[50:51] op_sel_hi:[1,0,1]
	v_pk_fma_f32 v[144:145], v[208:209], v[48:49], 0 op_sel_hi:[1,1,0]
	v_pk_fma_f32 v[54:55], v[168:169], v[216:217], v[54:55] op_sel_hi:[1,0,1] neg_lo:[0,1,0] neg_hi:[0,1,0]
	v_pk_fma_f32 v[144:145], v[210:211], v[50:51], v[144:145]
	v_pk_fma_f32 v[52:53], v[196:197], v[206:207], v[52:53] op_sel_hi:[1,0,1]
	v_add_f32_dpp v218, v217, v217 row_half_mirror row_mask:0xf bank_mask:0xf bound_ctrl:1
	v_pk_fma_f32 v[144:145], v[212:213], v[52:53], v[144:145]
	v_pk_fma_f32 v[54:55], v[198:199], v[206:207], v[54:55] op_sel_hi:[1,0,1]
	v_pk_fma_f32 v[56:57], v[160:161], v[218:219], v[56:57] op_sel_hi:[1,0,1] neg_lo:[0,1,0] neg_hi:[0,1,0]
	v_pk_fma_f32 v[144:145], v[214:215], v[54:55], v[144:145]
	s_nop 0
	v_add_f32_e32 v201, v144, v145
	v_mov_b32_e32 v144, v207
	v_pk_fma_f32 v[58:59], v[162:163], v[218:219], v[58:59] op_sel_hi:[1,0,1] neg_lo:[0,1,0] neg_hi:[0,1,0]
	v_pk_fma_f32 v[56:57], v[192:193], v[144:145], v[56:57] op_sel_hi:[1,0,1]
	v_pk_fma_f32 v[60:61], v[166:167], v[218:219], v[60:61] op_sel_hi:[1,0,1] neg_lo:[0,1,0] neg_hi:[0,1,0]
	v_pk_fma_f32 v[146:147], v[208:209], v[56:57], 0 op_sel_hi:[1,1,0]
	v_pk_fma_f32 v[58:59], v[194:195], v[144:145], v[58:59] op_sel_hi:[1,0,1]
	v_pk_fma_f32 v[62:63], v[168:169], v[218:219], v[62:63] op_sel_hi:[1,0,1] neg_lo:[0,1,0] neg_hi:[0,1,0]
	v_pk_fma_f32 v[146:147], v[210:211], v[58:59], v[146:147]
	v_pk_fma_f32 v[60:61], v[196:197], v[144:145], v[60:61] op_sel_hi:[1,0,1]
	s_nop 0
	v_pk_fma_f32 v[146:147], v[212:213], v[60:61], v[146:147]
	v_pk_fma_f32 v[62:63], v[198:199], v[144:145], v[62:63] op_sel_hi:[1,0,1]
	v_add_f32_dpp v143, v143, v143 quad_perm:[1,0,3,2] row_mask:0xf bank_mask:0xf bound_ctrl:1
	v_pk_fma_f32 v[144:145], v[214:215], v[62:63], v[146:147]
	v_add_f32_dpp v146, v200, v200 quad_perm:[1,0,3,2] row_mask:0xf bank_mask:0xf bound_ctrl:1
	v_add_f32_e32 v144, v144, v145
	v_add_f32_dpp v145, v151, v151 quad_perm:[1,0,3,2] row_mask:0xf bank_mask:0xf bound_ctrl:1
	v_add_f32_dpp v143, v143, v143 quad_perm:[2,3,0,1] row_mask:0xf bank_mask:0xf bound_ctrl:1
	v_add_f32_dpp v147, v150, v150 quad_perm:[1,0,3,2] row_mask:0xf bank_mask:0xf bound_ctrl:1
	v_add_f32_dpp v145, v145, v145 quad_perm:[2,3,0,1] row_mask:0xf bank_mask:0xf bound_ctrl:1
	v_add_f32_dpp v143, v143, v143 row_half_mirror row_mask:0xf bank_mask:0xf bound_ctrl:1
	v_add_f32_dpp v146, v146, v146 quad_perm:[2,3,0,1] row_mask:0xf bank_mask:0xf bound_ctrl:1
	v_add_f32_dpp v145, v145, v145 row_half_mirror row_mask:0xf bank_mask:0xf bound_ctrl:1
	v_cndmask_b32_e64 v143, 0, v143, s[6:7]
	v_add_f32_dpp v148, v164, v164 quad_perm:[1,0,3,2] row_mask:0xf bank_mask:0xf bound_ctrl:1
	v_add_f32_dpp v147, v147, v147 quad_perm:[2,3,0,1] row_mask:0xf bank_mask:0xf bound_ctrl:1
	v_add_f32_dpp v146, v146, v146 row_half_mirror row_mask:0xf bank_mask:0xf bound_ctrl:1
	v_cndmask_b32_e64 v143, v143, v145, s[8:9]
	v_add_f32_dpp v149, v170, v170 quad_perm:[1,0,3,2] row_mask:0xf bank_mask:0xf bound_ctrl:1
	v_add_f32_dpp v148, v148, v148 quad_perm:[2,3,0,1] row_mask:0xf bank_mask:0xf bound_ctrl:1
	v_add_f32_dpp v147, v147, v147 row_half_mirror row_mask:0xf bank_mask:0xf bound_ctrl:1
	v_cndmask_b32_e64 v143, v143, v146, s[10:11]
	v_add_f32_dpp v150, v201, v201 quad_perm:[1,0,3,2] row_mask:0xf bank_mask:0xf bound_ctrl:1
	v_add_f32_dpp v149, v149, v149 quad_perm:[2,3,0,1] row_mask:0xf bank_mask:0xf bound_ctrl:1
	v_add_f32_dpp v148, v148, v148 row_half_mirror row_mask:0xf bank_mask:0xf bound_ctrl:1
	v_cndmask_b32_e64 v143, v143, v147, s[12:13]
	v_add_f32_dpp v144, v144, v144 quad_perm:[1,0,3,2] row_mask:0xf bank_mask:0xf bound_ctrl:1
	v_add_f32_dpp v150, v150, v150 quad_perm:[2,3,0,1] row_mask:0xf bank_mask:0xf bound_ctrl:1
	v_add_f32_dpp v149, v149, v149 row_half_mirror row_mask:0xf bank_mask:0xf bound_ctrl:1
	v_cndmask_b32_e64 v143, v143, v148, s[14:15]
	v_add_f32_dpp v144, v144, v144 quad_perm:[2,3,0,1] row_mask:0xf bank_mask:0xf bound_ctrl:1
	v_add_f32_dpp v150, v150, v150 row_half_mirror row_mask:0xf bank_mask:0xf bound_ctrl:1
	v_cndmask_b32_e64 v143, v143, v149, s[16:17]
	v_add_f32_dpp v144, v144, v144 row_half_mirror row_mask:0xf bank_mask:0xf bound_ctrl:1
	v_cndmask_b32_e64 v143, v143, v150, s[18:19]
	v_cndmask_b32_e64 v143, v143, v144, s[20:21]
	v_bfe_u32 v144, v143, 16, 1
	v_add3_u32 v143, v143, v144, s82
	v_mad_i64_i32 v[144:145], s[46:47], s46, v190, v[88:89]
	global_store_short_d16_hi v[144:145], v143, off
	s_cbranch_scc0 .LBB0_999
; template <int MODE>
; __device__ __forceinline__ void scan_unit(const Params& p, int l, int chain, int chunk, float* wl) {
;     ...
;   for (int tile = 0; tile < ntiles; ++tile) {
;     asm volatile("s_waitcnt lgkmcnt(0)" ::: "memory");
; #pragma unroll
;     for (int s = 0; s < TS; ++s) {
;       float e = (float)pe[s], kk = (float)pkk[s], a = (float)pa[s];
;       lw[s * 64 + lane] = __expf(-e);
;       lkk[s * 64 + lane] = kk;
;       lbb[s * 64 + lane] = kk * a;
;       if (MODE >= 1) {
;         lkd[s * 64 + lane] = (float)pk[s] * (1.0f + (a - 1.0f) * ka);
;         lv[s * 64 + lane] = (float)pv[s];
;       }
;       if (MODE == 2) lr[s * 64 + lane] = (float)pr[s];
;     }
;     asm volatile("s_waitcnt lgkmcnt(0)" ::: "memory");
;     if (tile + 1 < ntiles) { SCAN_PREFETCH(tile + 1) }
; #pragma unroll 1
; __device__ __forceinline__ void phase_scanC(const Params& p, int l, float* smem) {
;     ...
;   for (int u = gw; u < NU; u += nw) {
;     int chain = u % 24, chunk = u / 24;
;     scan_unit<2>(p, l, chain, chunk, wl);
;   }
	ds_read_b128 v[152:155], v92 offset:1792
	ds_read_b128 v[156:159], v92 offset:1808
	s_waitcnt lgkmcnt(0)
	v_pk_mul_f32 v[4:5], v[4:5], v[152:153]
	v_pk_mul_f32 v[6:7], v[6:7], v[154:155]
	v_pk_mul_f32 v[0:1], v[0:1], v[156:157]
	v_pk_mul_f32 v[2:3], v[2:3], v[158:159]
	v_pk_mul_f32 v[14:15], v[14:15], v[154:155]
	v_pk_mul_f32 v[12:13], v[12:13], v[152:153]
	v_pk_mul_f32 v[8:9], v[8:9], v[156:157]
	v_pk_mul_f32 v[10:11], v[10:11], v[158:159]
	v_pk_mul_f32 v[18:19], v[18:19], v[154:155]
	v_pk_mul_f32 v[16:17], v[16:17], v[152:153]
	v_pk_mul_f32 v[20:21], v[20:21], v[156:157]
	v_pk_mul_f32 v[22:23], v[22:23], v[158:159]
	v_pk_mul_f32 v[24:25], v[24:25], v[152:153]
	v_pk_mul_f32 v[26:27], v[26:27], v[154:155]
	v_pk_mul_f32 v[28:29], v[28:29], v[156:157]
	v_pk_mul_f32 v[30:31], v[30:31], v[158:159]
	v_pk_mul_f32 v[34:35], v[34:35], v[154:155]
	v_pk_mul_f32 v[32:33], v[32:33], v[152:153]
	v_pk_mul_f32 v[36:37], v[36:37], v[156:157]
	v_pk_mul_f32 v[38:39], v[38:39], v[158:159]
	v_pk_mul_f32 v[42:43], v[42:43], v[154:155]
	v_pk_mul_f32 v[40:41], v[40:41], v[152:153]
	v_pk_mul_f32 v[44:45], v[44:45], v[156:157]
	v_pk_mul_f32 v[46:47], v[46:47], v[158:159]
	v_pk_mul_f32 v[50:51], v[50:51], v[154:155]
	v_pk_mul_f32 v[48:49], v[48:49], v[152:153]
	v_pk_mul_f32 v[52:53], v[52:53], v[156:157]
	v_pk_mul_f32 v[54:55], v[54:55], v[158:159]
	v_pk_mul_f32 v[56:57], v[56:57], v[152:153]
	v_pk_mul_f32 v[58:59], v[58:59], v[154:155]
	v_pk_mul_f32 v[60:61], v[60:61], v[156:157]
	v_pk_mul_f32 v[62:63], v[62:63], v[158:159]
	s_add_i32 s39, s39, 8
	s_add_i32 s41, s41, -8
	s_cmp_eq_u32 s25, 32
	s_cbranch_scc0 .LBB0_996
	s_add_i32 s5, s5, s28
	s_cmpk_lt_i32 s5, 0x618
	s_cbranch_scc1 .LBB0_992
